# conv output stores non-temporal (streamed, consumed next phase by other XCDs); on top of pipelined conv + prep_item prefetch
# speedup vs baseline: 1.0044x; 1.0044x over previous
; __device__ __forceinline__ unsigned pk_bf16(float a, float b) { f32x2 v = {a, b}; bf2_t r = __builtin_convertvector(v, bf2_t); return __builtin_bit_cast(unsigned, r); }
; __device__ __forceinline__ float bf_lo(unsigned u) { return __uint_as_float(u << 16); }
; __device__ __forceinline__ float bf_hi(unsigned u) { return __uint_as_float(u & 0xffff0000u); }
; __device__ void phase_conv(const Params& p, int l, int nrows) {
;     ...
;         for (int i = 0; i < 16; ++i) {
;             const bf16_t* np = gp + (size_t)(i + 1) * FF;
;             const bool v = (c0 + i + 1) < W;
;             R[0] = (v && up) ? *(const u32x4*)(np - (size_t)64 * FF) : zero; R[1] = v ? *(const u32x4*)np : zero; R[2] = (v && dn) ? *(const u32x4*)(np + (size_t)64 * FF) : zero;
;             float acc[8];
; #pragma unroll
;             for (int j = 0; j < 8; ++j) acc[j] = bias[j];
; #pragma unroll
;             for (int rr = 0; rr < 3; ++rr) {
; #pragma unroll
;                 for (int j = 0; j < 4; ++j) {
;                     acc[2 * j] += bf_lo(L[rr][j]) * tp[rr * 3 + 0][2 * j] + bf_lo(M[rr][j]) * tp[rr * 3 + 1][2 * j] + bf_lo(R[rr][j]) * tp[rr * 3 + 2][2 * j];
;                     acc[2 * j + 1] += bf_hi(L[rr][j]) * tp[rr * 3 + 0][2 * j + 1] + bf_hi(M[rr][j]) * tp[rr * 3 + 1][2 * j + 1] + bf_hi(R[rr][j]) * tp[rr * 3 + 2][2 * j + 1];
;                 }
;             }
;             bf16_t* ap = Aup + (size_t)(tok0 + i) * FF + f0;
;             const u32x4 av = __builtin_nontemporal_load((const u32x4*)ap);
;             u32x4 wv;
; #pragma unroll
;             for (int j = 0; j < 4; ++j) wv[j] = pk_bf16(bf_lo(av[j]) * gelu_f(acc[2 * j]), bf_hi(av[j]) * gelu_f(acc[2 * j + 1]));
;             *(u32x4*)ap = wv;
.Lconv_nopf:
	v_lshlrev_b32_e32 v148, 16, v104
	v_and_b32_e32 v149, 0xffff0000, v104
	v_pk_fma_f32 v[124:125], v[20:21], v[148:149], v[124:125]
	v_pk_mul_f32 v[148:149], v[28:29], v[164:165]
	v_lshlrev_b32_e32 v164, 16, v100
	v_pk_fma_f32 v[148:149], v[36:37], v[170:171], v[148:149]
	v_and_b32_e32 v165, 0xffff0000, v100
	v_pk_add_f32 v[124:125], v[80:81], v[124:125]
	v_pk_fma_f32 v[148:149], v[44:45], v[164:165], v[148:149]
	v_pk_mul_f32 v[126:127], v[56:57], v[126:127]
	v_pk_add_f32 v[124:125], v[124:125], v[148:149]
	v_pk_mul_f32 v[148:149], v[52:53], v[162:163]
	v_lshlrev_b32_e32 v162, 16, v96
	v_pk_fma_f32 v[148:149], v[60:61], v[168:169], v[148:149]
	v_and_b32_e32 v163, 0xffff0000, v96
	v_pk_fma_f32 v[148:149], v[68:69], v[162:163], v[148:149]
	v_pk_fma_f32 v[126:127], v[64:65], v[144:145], v[126:127]
	v_pk_add_f32 v[148:149], v[124:125], v[148:149]
	v_mov_b64_e32 v[124:125], s[90:91]
	v_fma_f32 v9, |v148|, s80, 1.0
	v_pk_mul_f32 v[164:165], v[148:149], v[148:149]
	v_rcp_f32_e32 v162, v9
	v_mul_f32_e32 v9, 0xbf38aa3b, v164
	v_exp_f32_e32 v164, v9
	v_fma_f32 v9, |v149|, s80, 1.0
	v_rcp_f32_e32 v163, v9
	v_mul_f32_e32 v9, 0xbf38aa3b, v165
	v_exp_f32_e32 v165, v9
	v_cmp_gt_f32_e32 vcc, 0, v148
	v_pk_fma_f32 v[170:171], v[162:163], s[68:69], v[124:125] op_sel_hi:[1,0,0]
	v_cmp_gt_f32_e64 s[0:1], 0, v149
	v_pk_fma_f32 v[170:171], v[162:163], v[170:171], s[44:45] op_sel_hi:[1,1,0]
	v_pk_mul_f32 v[116:117], v[34:35], v[116:117]
	v_pk_fma_f32 v[170:171], v[162:163], v[170:171], s[84:85] op_sel_hi:[1,1,0]
	v_pk_fma_f32 v[116:117], v[42:43], v[142:143], v[116:117]
	v_pk_fma_f32 v[170:171], v[162:163], v[170:171], s[64:65] op_sel_hi:[1,1,0]
	v_pk_mul_f32 v[114:115], v[58:59], v[114:115]
	v_pk_mul_f32 v[162:163], v[162:163], v[170:171]
	v_pk_fma_f32 v[112:113], v[66:67], v[112:113], v[114:115]
	v_pk_mul_f32 v[162:163], v[164:165], v[162:163]
	v_lshlrev_b32_e32 v114, 16, v99
	v_pk_mul_f32 v[164:165], v[148:149], v[162:163]
	v_pk_fma_f32 v[148:149], v[148:149], v[162:163], v[148:149] neg_lo:[1,0,0] neg_hi:[1,0,0]
	v_and_b32_e32 v115, 0xffff0000, v99
	v_cndmask_b32_e64 v149, v149, v165, s[0:1]
	v_cndmask_b32_e32 v148, v148, v164, vcc
	v_pk_fma_f32 v[112:113], v[74:75], v[114:115], v[112:113]
	s_add_u32 s88, s88, 0xb000
	s_addc_u32 s89, s89, 0
	v_add_u32_e32 v188, 8, v188
	s_cmp_eq_u32 s88, 0x16000
	s_nop 0
	v_lshlrev_b32_e32 v168, 16, v108
	v_and_b32_e32 v169, 0xffff0000, v108
	v_pk_mul_f32 v[148:149], v[148:149], v[168:169]
	v_lshlrev_b32_e32 v144, 16, v110
	v_cvt_pk_bf16_f32 v108, v148, v149
	v_pk_mul_f32 v[148:149], v[14:15], v[172:173]
	v_and_b32_e32 v145, 0xffff0000, v110
	v_pk_fma_f32 v[146:147], v[6:7], v[146:147], v[148:149]
	v_lshlrev_b32_e32 v148, 16, v105
	v_and_b32_e32 v149, 0xffff0000, v105
	v_pk_fma_f32 v[146:147], v[22:23], v[148:149], v[146:147]
	v_pk_mul_f32 v[148:149], v[30:31], v[160:161]
	v_lshlrev_b32_e32 v160, 16, v101
	v_pk_fma_f32 v[148:149], v[38:39], v[166:167], v[148:149]
	v_and_b32_e32 v161, 0xffff0000, v101
	v_pk_add_f32 v[146:147], v[82:83], v[146:147]
	v_pk_fma_f32 v[148:149], v[46:47], v[160:161], v[148:149]
	s_nop 0
	v_pk_add_f32 v[146:147], v[146:147], v[148:149]
	v_pk_mul_f32 v[148:149], v[54:55], v[158:159]
	v_lshlrev_b32_e32 v158, 16, v109
	v_pk_fma_f32 v[148:149], v[62:63], v[156:157], v[148:149]
	v_lshlrev_b32_e32 v156, 16, v97
	v_and_b32_e32 v157, 0xffff0000, v97
	v_pk_fma_f32 v[148:149], v[70:71], v[156:157], v[148:149]
	v_and_b32_e32 v159, 0xffff0000, v109
	v_pk_add_f32 v[146:147], v[146:147], v[148:149]
	s_nop 0
	v_fma_f32 v9, |v146|, s80, 1.0
	v_pk_mul_f32 v[156:157], v[146:147], v[146:147]
	v_rcp_f32_e32 v148, v9
	v_mul_f32_e32 v9, 0xbf38aa3b, v156
	v_exp_f32_e32 v156, v9
	v_fma_f32 v9, |v147|, s80, 1.0
	v_rcp_f32_e32 v149, v9
	v_mul_f32_e32 v9, 0xbf38aa3b, v157
	v_exp_f32_e32 v157, v9
	v_cmp_gt_f32_e32 vcc, 0, v146
	v_pk_fma_f32 v[160:161], v[148:149], s[68:69], v[124:125] op_sel_hi:[1,0,0]
	v_cmp_gt_f32_e64 s[0:1], 0, v147
	v_pk_fma_f32 v[160:161], v[148:149], v[160:161], s[44:45] op_sel_hi:[1,1,0]
	s_nop 0
	v_pk_fma_f32 v[160:161], v[148:149], v[160:161], s[84:85] op_sel_hi:[1,1,0]
	s_nop 0
; __device__ __forceinline__ unsigned pk_bf16(float a, float b) { f32x2 v = {a, b}; bf2_t r = __builtin_convertvector(v, bf2_t); return __builtin_bit_cast(unsigned, r); }
; __device__ __forceinline__ float bf_lo(unsigned u) { return __uint_as_float(u << 16); }
; __device__ __forceinline__ float bf_hi(unsigned u) { return __uint_as_float(u & 0xffff0000u); }
; __device__ void phase_conv(const Params& p, int l, int nrows) {
;     ...
;         for (int i = 0; i < 16; ++i) {
;             const bf16_t* np = gp + (size_t)(i + 1) * FF;
;             const bool v = (c0 + i + 1) < W;
;             R[0] = (v && up) ? *(const u32x4*)(np - (size_t)64 * FF) : zero; R[1] = v ? *(const u32x4*)np : zero; R[2] = (v && dn) ? *(const u32x4*)(np + (size_t)64 * FF) : zero;
;             float acc[8];
; #pragma unroll
;             for (int j = 0; j < 8; ++j) acc[j] = bias[j];
; #pragma unroll
;             for (int rr = 0; rr < 3; ++rr) {
; #pragma unroll
;                 for (int j = 0; j < 4; ++j) {
;                     acc[2 * j] += bf_lo(L[rr][j]) * tp[rr * 3 + 0][2 * j] + bf_lo(M[rr][j]) * tp[rr * 3 + 1][2 * j] + bf_lo(R[rr][j]) * tp[rr * 3 + 2][2 * j];
;                     acc[2 * j + 1] += bf_hi(L[rr][j]) * tp[rr * 3 + 0][2 * j + 1] + bf_hi(M[rr][j]) * tp[rr * 3 + 1][2 * j + 1] + bf_hi(R[rr][j]) * tp[rr * 3 + 2][2 * j + 1];
;                 }
;             }
;             bf16_t* ap = Aup + (size_t)(tok0 + i) * FF + f0;
;             const u32x4 av = __builtin_nontemporal_load((const u32x4*)ap);
;             u32x4 wv;
; #pragma unroll
;             for (int j = 0; j < 4; ++j) wv[j] = pk_bf16(bf_lo(av[j]) * gelu_f(acc[2 * j]), bf_hi(av[j]) * gelu_f(acc[2 * j + 1]));
;             *(u32x4*)ap = wv;
	v_pk_fma_f32 v[160:161], v[148:149], v[160:161], s[64:65] op_sel_hi:[1,1,0]
	s_nop 0
	v_pk_mul_f32 v[148:149], v[148:149], v[160:161]
	s_nop 0
	v_pk_mul_f32 v[148:149], v[156:157], v[148:149]
	s_nop 0
	v_pk_mul_f32 v[156:157], v[146:147], v[148:149]
	v_pk_fma_f32 v[146:147], v[146:147], v[148:149], v[146:147] neg_lo:[1,0,0] neg_hi:[1,0,0]
	s_nop 0
	v_cndmask_b32_e64 v147, v147, v157, s[0:1]
	v_cndmask_b32_e32 v146, v146, v156, vcc
	v_pk_mul_f32 v[146:147], v[146:147], v[158:159]
	s_nop 0
	v_cvt_pk_bf16_f32 v109, v146, v147
	v_pk_mul_f32 v[146:147], v[16:17], v[154:155]
	s_nop 0
	v_pk_fma_f32 v[128:129], v[0:1], v[128:129], v[146:147]
	v_lshlrev_b32_e32 v146, 16, v106
	v_and_b32_e32 v147, 0xffff0000, v106
	v_pk_fma_f32 v[128:129], v[24:25], v[146:147], v[128:129]
	v_lshlrev_b32_e32 v146, 16, v102
	v_and_b32_e32 v147, 0xffff0000, v102
	v_pk_add_f32 v[128:129], v[76:77], v[128:129]
	v_pk_fma_f32 v[140:141], v[48:49], v[146:147], v[140:141]
	s_nop 0
	v_pk_add_f32 v[128:129], v[128:129], v[140:141]
	v_lshlrev_b32_e32 v140, 16, v98
	v_and_b32_e32 v141, 0xffff0000, v98
	v_pk_fma_f32 v[126:127], v[72:73], v[140:141], v[126:127]
	s_nop 0
	v_pk_add_f32 v[126:127], v[128:129], v[126:127]
	s_nop 0
	v_fma_f32 v9, |v126|, s80, 1.0
	v_pk_mul_f32 v[140:141], v[126:127], v[126:127]
	v_rcp_f32_e32 v128, v9
	v_mul_f32_e32 v9, 0xbf38aa3b, v140
	v_exp_f32_e32 v140, v9
	v_fma_f32 v9, |v127|, s80, 1.0
	v_rcp_f32_e32 v129, v9
	v_mul_f32_e32 v9, 0xbf38aa3b, v141
	v_exp_f32_e32 v141, v9
	v_cmp_gt_f32_e32 vcc, 0, v126
	v_pk_fma_f32 v[146:147], v[128:129], s[68:69], v[124:125] op_sel_hi:[1,0,0]
	v_cmp_gt_f32_e64 s[0:1], 0, v127
	v_pk_fma_f32 v[146:147], v[128:129], v[146:147], s[44:45] op_sel_hi:[1,1,0]
	s_nop 0
	v_pk_fma_f32 v[146:147], v[128:129], v[146:147], s[84:85] op_sel_hi:[1,1,0]
	s_nop 0
	v_pk_fma_f32 v[146:147], v[128:129], v[146:147], s[64:65] op_sel_hi:[1,1,0]
	s_nop 0
	v_pk_mul_f32 v[128:129], v[128:129], v[146:147]
	s_nop 0
	v_pk_mul_f32 v[128:129], v[140:141], v[128:129]
	s_nop 0
	v_pk_mul_f32 v[140:141], v[126:127], v[128:129]
	v_pk_fma_f32 v[126:127], v[126:127], v[128:129], v[126:127] neg_lo:[1,0,0] neg_hi:[1,0,0]
	s_nop 0
	v_cndmask_b32_e64 v127, v127, v141, s[0:1]
	v_cndmask_b32_e32 v126, v126, v140, vcc
	v_pk_mul_f32 v[126:127], v[126:127], v[144:145]
	s_nop 0
	v_cvt_pk_bf16_f32 v110, v126, v127
	v_pk_mul_f32 v[126:127], v[18:19], v[152:153]
	s_nop 0
	v_pk_fma_f32 v[118:119], v[2:3], v[118:119], v[126:127]
	v_lshlrev_b32_e32 v126, 16, v107
	v_and_b32_e32 v127, 0xffff0000, v107
	v_pk_fma_f32 v[118:119], v[26:27], v[126:127], v[118:119]
	v_lshlrev_b32_e32 v126, 16, v103
	v_and_b32_e32 v127, 0xffff0000, v103
	v_pk_add_f32 v[118:119], v[78:79], v[118:119]
	v_pk_fma_f32 v[116:117], v[50:51], v[126:127], v[116:117]
	s_nop 0
	v_pk_add_f32 v[116:117], v[118:119], v[116:117]
	v_lshlrev_b32_e32 v118, 16, v111
	v_pk_add_f32 v[112:113], v[116:117], v[112:113]
	v_and_b32_e32 v119, 0xffff0000, v111
	v_fma_f32 v9, |v112|, s80, 1.0
	v_pk_mul_f32 v[116:117], v[112:113], v[112:113]
	v_rcp_f32_e32 v114, v9
	v_mul_f32_e32 v9, 0xbf38aa3b, v116
	v_exp_f32_e32 v116, v9
	v_fma_f32 v9, |v113|, s80, 1.0
	v_rcp_f32_e32 v115, v9
	v_mul_f32_e32 v9, 0xbf38aa3b, v117
	v_exp_f32_e32 v117, v9
	v_cmp_gt_f32_e32 vcc, 0, v112
	v_pk_fma_f32 v[124:125], v[114:115], s[68:69], v[124:125] op_sel_hi:[1,0,0]
	v_cmp_gt_f32_e64 s[0:1], 0, v113
	v_pk_fma_f32 v[124:125], v[114:115], v[124:125], s[44:45] op_sel_hi:[1,1,0]
	s_nop 0
	v_pk_fma_f32 v[124:125], v[114:115], v[124:125], s[84:85] op_sel_hi:[1,1,0]
	s_nop 0
	v_pk_fma_f32 v[124:125], v[114:115], v[124:125], s[64:65] op_sel_hi:[1,1,0]
	s_nop 0
	v_pk_mul_f32 v[114:115], v[114:115], v[124:125]
	s_nop 0
	v_pk_mul_f32 v[114:115], v[116:117], v[114:115]
	s_nop 0
	v_pk_mul_f32 v[116:117], v[112:113], v[114:115]
	v_pk_fma_f32 v[112:113], v[112:113], v[114:115], v[112:113] neg_lo:[1,0,0] neg_hi:[1,0,0]
	s_nop 0
	v_cndmask_b32_e64 v113, v113, v117, s[0:1]
	v_cndmask_b32_e32 v112, v112, v116, vcc
	v_pk_mul_f32 v[112:113], v[112:113], v[118:119]
	s_nop 0
	v_cvt_pk_bf16_f32 v111, v112, v113
	global_store_dwordx4 v[10:11], v[108:111], off offset:2560 nt
	s_cbranch_scc1 .LBB0_701

; __device__ void phase_conv(const Params& p, int l, int nrows) {
;     ...
;         for (int i = 0; i < 16; ++i) {
;             const bf16_t* np = gp + (size_t)(i + 1) * FF;
;             const bool v = (c0 + i + 1) < W;
;             R[0] = (v && up) ? *(const u32x4*)(np - (size_t)64 * FF) : zero; R[1] = v ? *(const u32x4*)np : zero; R[2] = (v && dn) ? *(const u32x4*)(np + (size_t)64 * FF) : zero;
;             float acc[8];
; #pragma unroll
;             for (int j = 0; j < 8; ++j) acc[j] = bias[j];
.LBB0_725:
	s_or_b64 exec, exec, s[66:67]
	s_mov_b32 s0, 0x7fad000
	v_add_co_u32_e32 v160, vcc, s0, v124
	s_waitcnt vmcnt(1)
	v_lshlrev_b32_e32 v10, 16, v92
	v_addc_co_u32_e32 v161, vcc, 0, v125, vcc
	v_lshlrev_b32_e32 v148, 16, v104
	v_and_b32_e32 v11, 0xffff0000, v92
	v_and_b32_e32 v149, 0xffff0000, v104
	v_lshlrev_b32_e32 v128, 16, v93
	v_lshlrev_b32_e32 v144, 16, v105
	v_and_b32_e32 v129, 0xffff0000, v93
	v_and_b32_e32 v145, 0xffff0000, v105
	v_lshlrev_b32_e32 v104, 16, v94
	v_and_b32_e32 v105, 0xffff0000, v94
	v_lshlrev_b32_e32 v146, 16, v95
	v_and_b32_e32 v147, 0xffff0000, v95
	v_lshlrev_b32_e32 v142, 16, v106
	v_and_b32_e32 v143, 0xffff0000, v106
	v_lshlrev_b32_e32 v140, 16, v107
	v_and_b32_e32 v141, 0xffff0000, v107
	v_pk_mul_f32 v[106:107], v[12:13], v[148:149]
	s_waitcnt vmcnt(1)
	v_mov_b64_e32 v[112:113], v[200:201]
	v_mov_b64_e32 v[114:115], v[202:203]
	v_mov_b64_e32 v[108:109], v[204:205]
	v_mov_b64_e32 v[110:111], v[206:207]
	v_mov_b64_e32 v[116:117], v[208:209]
	v_mov_b64_e32 v[118:119], v[210:211]
	v_mov_b64_e32 v[92:93], v[196:197]
	v_mov_b64_e32 v[94:95], v[198:199]
	v_add_u32_e32 v214, -6, v188
	v_cmp_lt_u32_e64 s[98:99], v214, v187
	s_add_u32 s100, s20, 0x7fae600
	s_addc_u32 s101, s21, 0
	global_load_dwordx4 v[196:199], v192, s[100:101] nt
	v_mov_b32_e32 v200, 0
	v_mov_b32_e32 v201, 0
	v_mov_b32_e32 v202, 0
	v_mov_b32_e32 v203, 0
	v_mov_b32_e32 v204, 0
	v_mov_b32_e32 v205, 0
	v_mov_b32_e32 v206, 0
	v_mov_b32_e32 v207, 0
	v_mov_b32_e32 v208, 0
	v_mov_b32_e32 v209, 0
	v_mov_b32_e32 v210, 0
	v_mov_b32_e32 v211, 0
	s_add_u32 s10, s20, 0x13aafc00
	s_addc_u32 s11, s21, 0
	s_and_saveexec_b64 s[22:23], s[98:99]
	global_load_dwordx4 v[204:207], v192, s[10:11]
	s_add_u32 s100, s20, 0x13a57c00
	s_addc_u32 s101, s21, 0
	s_and_b64 exec, exec, s[40:41]
	global_load_dwordx4 v[200:203], v192, s[100:101]
	s_add_u32 s10, s20, 0x13b07c00
	s_addc_u32 s11, s21, 0
	s_and_b64 exec, s[22:23], s[98:99]
	s_and_b64 exec, exec, s[42:43]
	global_load_dwordx4 v[208:211], v192, s[10:11]
	s_mov_b64 exec, s[22:23]
	v_lshlrev_b32_e32 v150, 16, v100
	v_pk_fma_f32 v[106:107], v[4:5], v[10:11], v[106:107]
	v_lshlrev_b32_e32 v10, 16, v112
	v_and_b32_e32 v11, 0xffff0000, v112
	v_pk_fma_f32 v[106:107], v[20:21], v[10:11], v[106:107]
	v_and_b32_e32 v151, 0xffff0000, v100
	v_pk_add_f32 v[126:127], v[80:81], v[106:107]
	v_lshlrev_b32_e32 v106, 16, v84
	v_and_b32_e32 v107, 0xffff0000, v84
	v_pk_mul_f32 v[106:107], v[28:29], v[106:107]
	v_lshlrev_b32_e32 v154, 16, v96
	v_pk_fma_f32 v[152:153], v[36:37], v[150:151], v[106:107]
	v_lshlrev_b32_e32 v106, 16, v108
	v_and_b32_e32 v107, 0xffff0000, v108
	v_pk_fma_f32 v[152:153], v[44:45], v[106:107], v[152:153]
	v_and_b32_e32 v155, 0xffff0000, v96
	v_pk_add_f32 v[152:153], v[126:127], v[152:153]
	v_lshlrev_b32_e32 v126, 16, v88
	v_and_b32_e32 v127, 0xffff0000, v88
	v_pk_mul_f32 v[126:127], v[52:53], v[126:127]
	v_mov_b64_e32 v[162:163], s[90:91]
	v_pk_fma_f32 v[156:157], v[60:61], v[154:155], v[126:127]
	v_lshlrev_b32_e32 v126, 16, v116
	v_and_b32_e32 v127, 0xffff0000, v116
	v_pk_fma_f32 v[156:157], v[68:69], v[126:127], v[156:157]
	v_lshlrev_b32_e32 v88, 16, v89
	v_pk_add_f32 v[152:153], v[152:153], v[156:157]
	v_and_b32_e32 v89, 0xffff0000, v89
	v_fma_f32 v9, |v152|, s80, 1.0
	v_pk_mul_f32 v[158:159], v[152:153], v[152:153]
	v_rcp_f32_e32 v156, v9
	v_mul_f32_e32 v9, 0xbf38aa3b, v158
	v_exp_f32_e32 v158, v9
	v_fma_f32 v9, |v153|, s80, 1.0
	v_rcp_f32_e32 v157, v9
	v_mul_f32_e32 v9, 0xbf38aa3b, v159
	v_exp_f32_e32 v159, v9
	v_cmp_gt_f32_e32 vcc, 0, v152
	v_pk_fma_f32 v[166:167], v[156:157], s[68:69], v[162:163] op_sel_hi:[1,0,0]
	v_cmp_gt_f32_e64 s[0:1], 0, v153
	v_pk_fma_f32 v[166:167], v[156:157], v[166:167], s[44:45] op_sel_hi:[1,1,0]
	v_lshlrev_b32_e32 v168, 16, v109
	v_pk_fma_f32 v[166:167], v[156:157], v[166:167], s[84:85] op_sel_hi:[1,1,0]
	v_and_b32_e32 v169, 0xffff0000, v109
	v_pk_fma_f32 v[166:167], v[156:157], v[166:167], s[64:65] op_sel_hi:[1,1,0]
	v_pk_mul_f32 v[88:89], v[54:55], v[88:89]
	v_pk_mul_f32 v[156:157], v[156:157], v[166:167]
	v_lshlrev_b32_e32 v174, 16, v97
	v_pk_mul_f32 v[156:157], v[158:159], v[156:157]
	v_and_b32_e32 v175, 0xffff0000, v97
	v_pk_mul_f32 v[158:159], v[152:153], v[156:157]
	v_pk_fma_f32 v[152:153], v[152:153], v[156:157], v[152:153] neg_lo:[1,0,0] neg_hi:[1,0,0]
	v_pk_fma_f32 v[88:89], v[62:63], v[174:175], v[88:89]
	v_cndmask_b32_e64 v153, v153, v159, s[0:1]
	v_cndmask_b32_e32 v152, v152, v158, vcc
	v_lshlrev_b32_e32 v158, 16, v101
	v_and_b32_e32 v159, 0xffff0000, v101
	v_lshlrev_b32_e32 v166, 16, v117
	v_and_b32_e32 v167, 0xffff0000, v117
	v_pk_fma_f32 v[88:89], v[70:71], v[166:167], v[88:89]
	v_lshlrev_b32_e32 v116, 16, v102
	v_and_b32_e32 v117, 0xffff0000, v102
	v_lshlrev_b32_e32 v102, 16, v111
	v_lshlrev_b32_e32 v170, 16, v99
	v_and_b32_e32 v171, 0xffff0000, v99
	s_nop 0
	v_lshlrev_b32_e32 v164, 16, v92
	v_and_b32_e32 v165, 0xffff0000, v92
	v_pk_mul_f32 v[152:153], v[152:153], v[164:165]
	s_nop 0
	v_cvt_pk_bf16_f32 v84, v152, v153
	v_pk_mul_f32 v[152:153], v[14:15], v[144:145]
	s_nop 0
	v_pk_fma_f32 v[152:153], v[6:7], v[128:129], v[152:153]
	v_lshlrev_b32_e32 v128, 16, v113
	v_and_b32_e32 v129, 0xffff0000, v113
	v_pk_fma_f32 v[112:113], v[22:23], v[128:129], v[152:153]
	v_lshlrev_b32_e32 v152, 16, v85
	v_and_b32_e32 v153, 0xffff0000, v85
	v_pk_mul_f32 v[152:153], v[30:31], v[152:153]
	v_pk_add_f32 v[112:113], v[82:83], v[112:113]
	v_pk_fma_f32 v[100:101], v[38:39], v[158:159], v[152:153]
	v_lshlrev_b32_e32 v152, 16, v98
	v_pk_fma_f32 v[100:101], v[46:47], v[168:169], v[100:101]
	v_and_b32_e32 v153, 0xffff0000, v98
	v_pk_add_f32 v[100:101], v[112:113], v[100:101]
; __device__ __forceinline__ unsigned pk_bf16(float a, float b) { f32x2 v = {a, b}; bf2_t r = __builtin_convertvector(v, bf2_t); return __builtin_bit_cast(unsigned, r); }
; __device__ __forceinline__ float bf_lo(unsigned u) { return __uint_as_float(u << 16); }
; __device__ __forceinline__ float bf_hi(unsigned u) { return __uint_as_float(u & 0xffff0000u); }
; __device__ void phase_conv(const Params& p, int l, int nrows) {
;     ...
; #pragma unroll
;             for (int rr = 0; rr < 3; ++rr) {
; #pragma unroll
;                 for (int j = 0; j < 4; ++j) {
;                     acc[2 * j] += bf_lo(L[rr][j]) * tp[rr * 3 + 0][2 * j] + bf_lo(M[rr][j]) * tp[rr * 3 + 1][2 * j] + bf_lo(R[rr][j]) * tp[rr * 3 + 2][2 * j];
;                     acc[2 * j + 1] += bf_hi(L[rr][j]) * tp[rr * 3 + 0][2 * j + 1] + bf_hi(M[rr][j]) * tp[rr * 3 + 1][2 * j + 1] + bf_hi(R[rr][j]) * tp[rr * 3 + 2][2 * j + 1];
;                 }
;             }
;             bf16_t* ap = Aup + (size_t)(tok0 + i) * FF + f0;
;             const u32x4 av = __builtin_nontemporal_load((const u32x4*)ap);
;             u32x4 wv;
; #pragma unroll
;             for (int j = 0; j < 4; ++j) wv[j] = pk_bf16(bf_lo(av[j]) * gelu_f(acc[2 * j]), bf_hi(av[j]) * gelu_f(acc[2 * j + 1]));
;             *(u32x4*)ap = wv;
; #pragma unroll
;             for (int rr = 0; rr < 3; ++rr) { L[rr] = M[rr]; M[rr] = R[rr]; }
;         }
	v_lshlrev_b32_e32 v112, 16, v94
	v_pk_add_f32 v[88:89], v[100:101], v[88:89]
	v_lshlrev_b32_e32 v100, 16, v93
	v_fma_f32 v9, |v88|, s80, 1.0
	v_pk_mul_f32 v[96:97], v[88:89], v[88:89]
	v_rcp_f32_e32 v92, v9
	v_mul_f32_e32 v9, 0xbf38aa3b, v96
	v_exp_f32_e32 v96, v9
	v_fma_f32 v9, |v89|, s80, 1.0
	v_and_b32_e32 v101, 0xffff0000, v93
	v_rcp_f32_e32 v93, v9
	v_mul_f32_e32 v9, 0xbf38aa3b, v97
	v_exp_f32_e32 v97, v9
	v_cmp_gt_f32_e32 vcc, 0, v88
	v_pk_fma_f32 v[108:109], v[92:93], s[68:69], v[162:163] op_sel_hi:[1,0,0]
	v_cmp_gt_f32_e64 s[0:1], 0, v89
	v_pk_fma_f32 v[108:109], v[92:93], v[108:109], s[44:45] op_sel_hi:[1,1,0]
	v_and_b32_e32 v113, 0xffff0000, v94
	v_pk_fma_f32 v[108:109], v[92:93], v[108:109], s[84:85] op_sel_hi:[1,1,0]
	v_lshlrev_b32_e32 v94, 16, v95
	v_pk_fma_f32 v[108:109], v[92:93], v[108:109], s[64:65] op_sel_hi:[1,1,0]
	v_and_b32_e32 v95, 0xffff0000, v95
	v_pk_mul_f32 v[92:93], v[92:93], v[108:109]
	v_lshlrev_b32_e32 v108, 16, v118
	v_pk_mul_f32 v[92:93], v[96:97], v[92:93]
	v_and_b32_e32 v109, 0xffff0000, v118
	v_pk_mul_f32 v[96:97], v[88:89], v[92:93]
	v_pk_fma_f32 v[88:89], v[88:89], v[92:93], v[88:89] neg_lo:[1,0,0] neg_hi:[1,0,0]
	v_lshlrev_b32_e32 v92, 16, v86
	v_cndmask_b32_e64 v89, v89, v97, s[0:1]
	v_cndmask_b32_e32 v88, v88, v96, vcc
	v_pk_mul_f32 v[88:89], v[88:89], v[100:101]
	v_and_b32_e32 v93, 0xffff0000, v86
	v_cvt_pk_bf16_f32 v85, v88, v89
	v_pk_mul_f32 v[88:89], v[16:17], v[142:143]
	v_lshlrev_b32_e32 v100, 16, v114
	v_pk_fma_f32 v[88:89], v[0:1], v[104:105], v[88:89]
	v_and_b32_e32 v101, 0xffff0000, v114
	v_pk_mul_f32 v[92:93], v[32:33], v[92:93]
	v_pk_fma_f32 v[88:89], v[24:25], v[100:101], v[88:89]
	v_pk_fma_f32 v[92:93], v[40:41], v[116:117], v[92:93]
	v_lshlrev_b32_e32 v104, 16, v110
	v_and_b32_e32 v105, 0xffff0000, v110
	v_pk_add_f32 v[88:89], v[76:77], v[88:89]
	v_pk_fma_f32 v[92:93], v[48:49], v[104:105], v[92:93]
	s_nop 0
	v_pk_add_f32 v[88:89], v[88:89], v[92:93]
	v_lshlrev_b32_e32 v92, 16, v90
	v_and_b32_e32 v93, 0xffff0000, v90
	v_pk_mul_f32 v[92:93], v[56:57], v[92:93]
	v_lshlrev_b32_e32 v90, 16, v91
	v_pk_fma_f32 v[92:93], v[64:65], v[152:153], v[92:93]
	v_and_b32_e32 v91, 0xffff0000, v91
	v_pk_fma_f32 v[92:93], v[72:73], v[108:109], v[92:93]
	v_pk_mul_f32 v[90:91], v[58:59], v[90:91]
	v_pk_add_f32 v[88:89], v[88:89], v[92:93]
	v_pk_fma_f32 v[90:91], v[66:67], v[170:171], v[90:91]
	v_fma_f32 v9, |v88|, s80, 1.0
	v_pk_mul_f32 v[96:97], v[88:89], v[88:89]
	v_rcp_f32_e32 v92, v9
	v_mul_f32_e32 v9, 0xbf38aa3b, v96
	v_exp_f32_e32 v96, v9
	v_fma_f32 v9, |v89|, s80, 1.0
	v_rcp_f32_e32 v93, v9
	v_mul_f32_e32 v9, 0xbf38aa3b, v97
	v_exp_f32_e32 v97, v9
	v_cmp_gt_f32_e32 vcc, 0, v88
	v_pk_fma_f32 v[156:157], v[92:93], s[68:69], v[162:163] op_sel_hi:[1,0,0]
	v_cmp_gt_f32_e64 s[0:1], 0, v89
	v_pk_fma_f32 v[156:157], v[92:93], v[156:157], s[44:45] op_sel_hi:[1,1,0]
	s_nop 0
	v_pk_fma_f32 v[156:157], v[92:93], v[156:157], s[84:85] op_sel_hi:[1,1,0]
	s_nop 0
	v_pk_fma_f32 v[156:157], v[92:93], v[156:157], s[64:65] op_sel_hi:[1,1,0]
	s_nop 0
	v_pk_mul_f32 v[92:93], v[92:93], v[156:157]
	v_lshlrev_b32_e32 v156, 16, v103
	v_pk_mul_f32 v[92:93], v[96:97], v[92:93]
	v_and_b32_e32 v157, 0xffff0000, v103
	v_pk_mul_f32 v[96:97], v[88:89], v[92:93]
	v_pk_fma_f32 v[88:89], v[88:89], v[92:93], v[88:89] neg_lo:[1,0,0] neg_hi:[1,0,0]
	v_lshlrev_b32_e32 v92, 16, v87
	v_cndmask_b32_e64 v89, v89, v97, s[0:1]
	v_cndmask_b32_e32 v88, v88, v96, vcc
	v_pk_mul_f32 v[88:89], v[88:89], v[112:113]
	v_and_b32_e32 v93, 0xffff0000, v87
	v_cvt_pk_bf16_f32 v86, v88, v89
	v_pk_mul_f32 v[88:89], v[18:19], v[140:141]
	v_lshlrev_b32_e32 v112, 16, v115
	v_pk_fma_f32 v[88:89], v[2:3], v[146:147], v[88:89]
	v_and_b32_e32 v113, 0xffff0000, v115
	v_pk_mul_f32 v[92:93], v[34:35], v[92:93]
	v_pk_fma_f32 v[88:89], v[26:27], v[112:113], v[88:89]
	v_pk_fma_f32 v[92:93], v[42:43], v[156:157], v[92:93]
	v_and_b32_e32 v103, 0xffff0000, v111
	v_pk_add_f32 v[88:89], v[78:79], v[88:89]
	v_pk_fma_f32 v[92:93], v[50:51], v[102:103], v[92:93]
	v_lshlrev_b32_e32 v146, 16, v119
	v_and_b32_e32 v147, 0xffff0000, v119
	v_pk_add_f32 v[88:89], v[88:89], v[92:93]
	v_pk_fma_f32 v[90:91], v[74:75], v[146:147], v[90:91]
	s_nop 0
	v_pk_add_f32 v[88:89], v[88:89], v[90:91]
	s_nop 0
	v_fma_f32 v9, |v88|, s80, 1.0
	v_pk_mul_f32 v[92:93], v[88:89], v[88:89]
	v_rcp_f32_e32 v90, v9
	v_mul_f32_e32 v9, 0xbf38aa3b, v92
	v_exp_f32_e32 v92, v9
	v_fma_f32 v9, |v89|, s80, 1.0
	v_rcp_f32_e32 v91, v9
	v_mul_f32_e32 v9, 0xbf38aa3b, v93
	v_exp_f32_e32 v93, v9
	v_cmp_gt_f32_e32 vcc, 0, v88
	v_pk_fma_f32 v[96:97], v[90:91], s[68:69], v[162:163] op_sel_hi:[1,0,0]
	v_cmp_gt_f32_e64 s[0:1], 0, v89
	v_pk_fma_f32 v[96:97], v[90:91], v[96:97], s[44:45] op_sel_hi:[1,1,0]
	v_add_u32_e32 v9, -6, v188
	v_pk_fma_f32 v[96:97], v[90:91], v[96:97], s[84:85] op_sel_hi:[1,1,0]
	s_nop 0
	v_pk_fma_f32 v[96:97], v[90:91], v[96:97], s[64:65] op_sel_hi:[1,1,0]
	s_nop 0
	v_pk_mul_f32 v[90:91], v[90:91], v[96:97]
	s_nop 0
	v_pk_mul_f32 v[90:91], v[92:93], v[90:91]
	s_nop 0
	v_pk_mul_f32 v[92:93], v[88:89], v[90:91]
	v_pk_fma_f32 v[88:89], v[88:89], v[90:91], v[88:89] neg_lo:[1,0,0] neg_hi:[1,0,0]
	v_mov_b32_e32 v90, 0
	v_cndmask_b32_e64 v89, v89, v93, s[0:1]
	v_cndmask_b32_e32 v88, v88, v92, vcc
	v_pk_mul_f32 v[88:89], v[88:89], v[94:95]
	v_cmp_lt_u32_e64 s[0:1], v9, v187
	v_cvt_pk_bf16_f32 v87, v88, v89
	global_store_dwordx4 v[160:161], v[84:87], off nt
	s_and_b64 s[6:7], s[0:1], s[40:41]
	v_mov_b32_e32 v88, 0
	v_mov_b32_e32 v84, 0
	v_mov_b32_e32 v89, 0
	v_mov_b32_e32 v91, 0
	s_and_saveexec_b64 s[66:67], s[6:7]
	s_cbranch_execz .LBB0_727
	v_add_co_u32_e32 v86, vcc, 0x13a57000, v124
	s_nop 1
	v_addc_co_u32_e32 v87, vcc, 0, v125, vcc

; __device__ void phase_conv(const Params& p, int l, int nrows) {
;     ...
;         for (int i = 0; i < 16; ++i) {
;             const bf16_t* np = gp + (size_t)(i + 1) * FF;
;             const bool v = (c0 + i + 1) < W;
;             R[0] = (v && up) ? *(const u32x4*)(np - (size_t)64 * FF) : zero; R[1] = v ? *(const u32x4*)np : zero; R[2] = (v && dn) ? *(const u32x4*)(np + (size_t)64 * FF) : zero;
;             float acc[8];
; #pragma unroll
;             for (int j = 0; j < 8; ++j) acc[j] = bias[j];
.LBB0_731:
	s_or_b64 exec, exec, s[66:67]
	v_add_co_u32_e32 v172, vcc, 0x7fae000, v124
	v_pk_mul_f32 v[110:111], v[12:13], v[10:11]
	s_nop 0
	v_addc_co_u32_e32 v173, vcc, 0, v125, vcc
	v_pk_fma_f32 v[110:111], v[4:5], v[148:149], v[110:111]
	s_waitcnt vmcnt(1)
	v_mov_b64_e32 v[88:89], v[200:201]
	v_mov_b64_e32 v[90:91], v[202:203]
	v_mov_b64_e32 v[84:85], v[204:205]
	v_mov_b64_e32 v[86:87], v[206:207]
	v_mov_b64_e32 v[92:93], v[208:209]
	v_mov_b64_e32 v[94:95], v[210:211]
	v_mov_b64_e32 v[96:97], v[196:197]
	v_mov_b64_e32 v[98:99], v[198:199]
	v_add_u32_e32 v214, -5, v188
	v_cmp_lt_u32_e64 s[98:99], v214, v187
	s_add_u32 s100, s20, 0x7fafc00
	s_addc_u32 s101, s21, 0
	global_load_dwordx4 v[196:199], v192, s[100:101] nt
	v_mov_b32_e32 v200, 0
	v_mov_b32_e32 v201, 0
	v_mov_b32_e32 v202, 0
	v_mov_b32_e32 v203, 0
	v_mov_b32_e32 v204, 0
	v_mov_b32_e32 v205, 0
	v_mov_b32_e32 v206, 0
	v_mov_b32_e32 v207, 0
	v_mov_b32_e32 v208, 0
	v_mov_b32_e32 v209, 0
	v_mov_b32_e32 v210, 0
	v_mov_b32_e32 v211, 0
	s_add_u32 s10, s20, 0x13ab1200
	s_addc_u32 s11, s21, 0
	s_and_saveexec_b64 s[22:23], s[98:99]
	global_load_dwordx4 v[204:207], v192, s[10:11]
	s_add_u32 s100, s20, 0x13a59200
	s_addc_u32 s101, s21, 0
	s_and_b64 exec, exec, s[40:41]
	global_load_dwordx4 v[200:203], v192, s[100:101]
	s_add_u32 s10, s20, 0x13b09200
	s_addc_u32 s11, s21, 0
	s_and_b64 exec, s[22:23], s[98:99]
	s_and_b64 exec, exec, s[42:43]
	global_load_dwordx4 v[208:211], v192, s[10:11]
	s_mov_b64 exec, s[22:23]
	v_lshlrev_b32_e32 v148, 16, v88
	v_and_b32_e32 v149, 0xffff0000, v88
	v_pk_mul_f32 v[114:115], v[28:29], v[150:151]
	v_pk_fma_f32 v[110:111], v[20:21], v[148:149], v[110:111]
	v_pk_fma_f32 v[114:115], v[36:37], v[106:107], v[114:115]
	v_lshlrev_b32_e32 v164, 16, v84
	v_and_b32_e32 v165, 0xffff0000, v84
	v_pk_add_f32 v[110:111], v[80:81], v[110:111]
	v_pk_fma_f32 v[114:115], v[44:45], v[164:165], v[114:115]
	v_lshlrev_b32_e32 v162, 16, v92
	v_pk_add_f32 v[110:111], v[110:111], v[114:115]
	v_pk_mul_f32 v[114:115], v[52:53], v[154:155]
	v_and_b32_e32 v163, 0xffff0000, v92
	v_pk_fma_f32 v[114:115], v[60:61], v[126:127], v[114:115]
	v_mov_b64_e32 v[150:151], s[90:91]
	v_pk_fma_f32 v[114:115], v[68:69], v[162:163], v[114:115]
	s_nop 0
	v_lshlrev_b32_e32 v154, 16, v96
	v_pk_add_f32 v[110:111], v[110:111], v[114:115]
	v_and_b32_e32 v155, 0xffff0000, v96
	v_fma_f32 v9, |v110|, s80, 1.0
	v_pk_mul_f32 v[118:119], v[110:111], v[110:111]
	v_rcp_f32_e32 v114, v9
	v_mul_f32_e32 v9, 0xbf38aa3b, v118
	v_exp_f32_e32 v118, v9
	v_fma_f32 v9, |v111|, s80, 1.0
	v_rcp_f32_e32 v115, v9
	v_mul_f32_e32 v9, 0xbf38aa3b, v119
	v_exp_f32_e32 v119, v9
	v_cmp_gt_f32_e32 vcc, 0, v110
	v_pk_fma_f32 v[160:161], v[114:115], s[68:69], v[150:151] op_sel_hi:[1,0,0]
	v_cmp_gt_f32_e64 s[0:1], 0, v111
	v_pk_fma_f32 v[160:161], v[114:115], v[160:161], s[44:45] op_sel_hi:[1,1,0]
	s_nop 0
	v_pk_fma_f32 v[160:161], v[114:115], v[160:161], s[84:85] op_sel_hi:[1,1,0]
	s_nop 0
	v_pk_fma_f32 v[160:161], v[114:115], v[160:161], s[64:65] op_sel_hi:[1,1,0]
	s_nop 0
	v_pk_mul_f32 v[114:115], v[114:115], v[160:161]
	v_lshlrev_b32_e32 v160, 16, v85
	v_pk_mul_f32 v[114:115], v[118:119], v[114:115]
	v_and_b32_e32 v161, 0xffff0000, v85
	v_pk_mul_f32 v[118:119], v[110:111], v[114:115]
	v_pk_fma_f32 v[110:111], v[110:111], v[114:115], v[110:111] neg_lo:[1,0,0] neg_hi:[1,0,0]
	v_lshlrev_b32_e32 v114, 16, v97
	v_cndmask_b32_e64 v111, v111, v119, s[0:1]
	v_cndmask_b32_e32 v110, v110, v118, vcc
	v_pk_mul_f32 v[110:111], v[110:111], v[154:155]
	v_lshlrev_b32_e32 v154, 16, v89
	v_cvt_pk_bf16_f32 v84, v110, v111
	v_pk_mul_f32 v[110:111], v[14:15], v[128:129]
	v_and_b32_e32 v155, 0xffff0000, v89
	v_pk_fma_f32 v[110:111], v[6:7], v[144:145], v[110:111]
	v_and_b32_e32 v115, 0xffff0000, v97
	v_pk_fma_f32 v[88:89], v[22:23], v[154:155], v[110:111]
	v_pk_mul_f32 v[110:111], v[30:31], v[158:159]
	v_pk_add_f32 v[88:89], v[82:83], v[88:89]
	v_pk_fma_f32 v[110:111], v[38:39], v[168:169], v[110:111]
	v_lshlrev_b32_e32 v158, 16, v93
	v_pk_fma_f32 v[110:111], v[46:47], v[160:161], v[110:111]
	v_and_b32_e32 v159, 0xffff0000, v93
	v_pk_add_f32 v[88:89], v[88:89], v[110:111]
	v_pk_mul_f32 v[110:111], v[54:55], v[174:175]
	v_lshlrev_b32_e32 v144, 16, v86
	v_pk_fma_f32 v[110:111], v[62:63], v[166:167], v[110:111]
	v_and_b32_e32 v145, 0xffff0000, v86
	v_pk_fma_f32 v[92:93], v[70:71], v[158:159], v[110:111]
	s_nop 0
	v_pk_add_f32 v[88:89], v[88:89], v[92:93]
	s_nop 0
	v_fma_f32 v9, |v88|, s80, 1.0
	v_pk_mul_f32 v[110:111], v[88:89], v[88:89]
	v_rcp_f32_e32 v92, v9
	v_mul_f32_e32 v9, 0xbf38aa3b, v110
	v_exp_f32_e32 v96, v9
	v_fma_f32 v9, |v89|, s80, 1.0
	v_rcp_f32_e32 v93, v9
	v_mul_f32_e32 v9, 0xbf38aa3b, v111
	v_exp_f32_e32 v97, v9
	v_cmp_gt_f32_e32 vcc, 0, v88
	v_pk_fma_f32 v[118:119], v[92:93], s[68:69], v[150:151] op_sel_hi:[1,0,0]
	v_cmp_gt_f32_e64 s[0:1], 0, v89
; __device__ __forceinline__ unsigned pk_bf16(float a, float b) { f32x2 v = {a, b}; bf2_t r = __builtin_convertvector(v, bf2_t); return __builtin_bit_cast(unsigned, r); }
; __device__ __forceinline__ float bf_lo(unsigned u) { return __uint_as_float(u << 16); }
; __device__ __forceinline__ float bf_hi(unsigned u) { return __uint_as_float(u & 0xffff0000u); }
; __device__ void phase_conv(const Params& p, int l, int nrows) {
;     ...
; #pragma unroll
;             for (int rr = 0; rr < 3; ++rr) {
; #pragma unroll
;                 for (int j = 0; j < 4; ++j) {
;                     acc[2 * j] += bf_lo(L[rr][j]) * tp[rr * 3 + 0][2 * j] + bf_lo(M[rr][j]) * tp[rr * 3 + 1][2 * j] + bf_lo(R[rr][j]) * tp[rr * 3 + 2][2 * j];
;                     acc[2 * j + 1] += bf_hi(L[rr][j]) * tp[rr * 3 + 0][2 * j + 1] + bf_hi(M[rr][j]) * tp[rr * 3 + 1][2 * j + 1] + bf_hi(R[rr][j]) * tp[rr * 3 + 2][2 * j + 1];
;                 }
;             }
;             bf16_t* ap = Aup + (size_t)(tok0 + i) * FF + f0;
;             const u32x4 av = __builtin_nontemporal_load((const u32x4*)ap);
;             u32x4 wv;
; #pragma unroll
;             for (int j = 0; j < 4; ++j) wv[j] = pk_bf16(bf_lo(av[j]) * gelu_f(acc[2 * j]), bf_hi(av[j]) * gelu_f(acc[2 * j + 1]));
;             *(u32x4*)ap = wv;
; #pragma unroll
;             for (int rr = 0; rr < 3; ++rr) { L[rr] = M[rr]; M[rr] = R[rr]; }
;         }
	v_pk_fma_f32 v[118:119], v[92:93], v[118:119], s[44:45] op_sel_hi:[1,1,0]
	v_lshlrev_b32_e32 v110, 16, v98
	v_pk_fma_f32 v[118:119], v[92:93], v[118:119], s[84:85] op_sel_hi:[1,1,0]
	v_and_b32_e32 v111, 0xffff0000, v98
	v_pk_fma_f32 v[118:119], v[92:93], v[118:119], s[64:65] op_sel_hi:[1,1,0]
	s_nop 0
	v_pk_mul_f32 v[92:93], v[92:93], v[118:119]
	v_lshlrev_b32_e32 v118, 16, v94
	v_pk_mul_f32 v[92:93], v[96:97], v[92:93]
	v_and_b32_e32 v119, 0xffff0000, v94
	v_pk_mul_f32 v[96:97], v[88:89], v[92:93]
	v_pk_fma_f32 v[88:89], v[88:89], v[92:93], v[88:89] neg_lo:[1,0,0] neg_hi:[1,0,0]
	v_pk_mul_f32 v[92:93], v[32:33], v[116:117]
	v_cndmask_b32_e64 v89, v89, v97, s[0:1]
	v_cndmask_b32_e32 v88, v88, v96, vcc
	v_pk_mul_f32 v[88:89], v[88:89], v[114:115]
	v_lshlrev_b32_e32 v114, 16, v90
	v_cvt_pk_bf16_f32 v85, v88, v89
	v_pk_mul_f32 v[88:89], v[16:17], v[100:101]
	v_and_b32_e32 v115, 0xffff0000, v90
	v_pk_fma_f32 v[88:89], v[0:1], v[142:143], v[88:89]
	v_pk_fma_f32 v[92:93], v[40:41], v[104:105], v[92:93]
	v_pk_fma_f32 v[88:89], v[24:25], v[114:115], v[88:89]
	v_pk_fma_f32 v[92:93], v[48:49], v[144:145], v[92:93]
	v_pk_add_f32 v[88:89], v[76:77], v[88:89]
	v_lshlrev_b32_e32 v142, 16, v95
	v_pk_add_f32 v[88:89], v[88:89], v[92:93]
	v_pk_mul_f32 v[92:93], v[56:57], v[152:153]
	v_and_b32_e32 v143, 0xffff0000, v95
	v_pk_fma_f32 v[92:93], v[64:65], v[108:109], v[92:93]
	v_lshlrev_b32_e32 v94, 16, v99
	v_pk_fma_f32 v[92:93], v[72:73], v[118:119], v[92:93]
	v_and_b32_e32 v95, 0xffff0000, v99
	v_pk_add_f32 v[88:89], v[88:89], v[92:93]
	s_nop 0
	v_fma_f32 v9, |v88|, s80, 1.0
	v_pk_mul_f32 v[96:97], v[88:89], v[88:89]
	v_rcp_f32_e32 v92, v9
	v_mul_f32_e32 v9, 0xbf38aa3b, v96
	v_exp_f32_e32 v96, v9
	v_fma_f32 v9, |v89|, s80, 1.0
	v_rcp_f32_e32 v93, v9
	v_mul_f32_e32 v9, 0xbf38aa3b, v97
	v_exp_f32_e32 v97, v9
	v_cmp_gt_f32_e32 vcc, 0, v88
	v_pk_fma_f32 v[116:117], v[92:93], s[68:69], v[150:151] op_sel_hi:[1,0,0]
	v_cmp_gt_f32_e64 s[0:1], 0, v89
	v_pk_fma_f32 v[116:117], v[92:93], v[116:117], s[44:45] op_sel_hi:[1,1,0]
	s_nop 0
	v_pk_fma_f32 v[116:117], v[92:93], v[116:117], s[84:85] op_sel_hi:[1,1,0]
	s_nop 0
	v_pk_fma_f32 v[116:117], v[92:93], v[116:117], s[64:65] op_sel_hi:[1,1,0]
	s_nop 0
	v_pk_mul_f32 v[92:93], v[92:93], v[116:117]
	v_lshlrev_b32_e32 v116, 16, v87
	v_pk_mul_f32 v[92:93], v[96:97], v[92:93]
	v_and_b32_e32 v117, 0xffff0000, v87
	v_pk_mul_f32 v[96:97], v[88:89], v[92:93]
	v_pk_fma_f32 v[88:89], v[88:89], v[92:93], v[88:89] neg_lo:[1,0,0] neg_hi:[1,0,0]
	s_nop 0
	v_cndmask_b32_e64 v89, v89, v97, s[0:1]
	v_cndmask_b32_e32 v88, v88, v96, vcc
	v_pk_mul_f32 v[88:89], v[88:89], v[110:111]
	v_lshlrev_b32_e32 v110, 16, v91
	v_cvt_pk_bf16_f32 v86, v88, v89
	v_pk_mul_f32 v[88:89], v[18:19], v[112:113]
	v_and_b32_e32 v111, 0xffff0000, v91
	v_pk_fma_f32 v[88:89], v[2:3], v[140:141], v[88:89]
	v_pk_mul_f32 v[90:91], v[34:35], v[156:157]
	v_pk_fma_f32 v[88:89], v[26:27], v[110:111], v[88:89]
	v_pk_fma_f32 v[90:91], v[42:43], v[102:103], v[90:91]
	v_pk_add_f32 v[88:89], v[78:79], v[88:89]
	v_pk_fma_f32 v[90:91], v[50:51], v[116:117], v[90:91]
	s_nop 0
	v_pk_add_f32 v[88:89], v[88:89], v[90:91]
	v_pk_mul_f32 v[90:91], v[58:59], v[170:171]
	s_nop 0
	v_pk_fma_f32 v[90:91], v[66:67], v[146:147], v[90:91]
	s_nop 0
	v_pk_fma_f32 v[90:91], v[74:75], v[142:143], v[90:91]
	s_nop 0
	v_pk_add_f32 v[88:89], v[88:89], v[90:91]
	s_nop 0
	v_fma_f32 v9, |v88|, s80, 1.0
	v_pk_mul_f32 v[92:93], v[88:89], v[88:89]
	v_rcp_f32_e32 v90, v9
	v_mul_f32_e32 v9, 0xbf38aa3b, v92
	v_exp_f32_e32 v92, v9
	v_fma_f32 v9, |v89|, s80, 1.0
	v_rcp_f32_e32 v91, v9
	v_mul_f32_e32 v9, 0xbf38aa3b, v93
	v_exp_f32_e32 v93, v9
	v_cmp_gt_f32_e32 vcc, 0, v88
	v_pk_fma_f32 v[96:97], v[90:91], s[68:69], v[150:151] op_sel_hi:[1,0,0]
	v_cmp_gt_f32_e64 s[0:1], 0, v89
	v_pk_fma_f32 v[96:97], v[90:91], v[96:97], s[44:45] op_sel_hi:[1,1,0]
	v_add_u32_e32 v9, -5, v188
	v_pk_fma_f32 v[96:97], v[90:91], v[96:97], s[84:85] op_sel_hi:[1,1,0]
	s_nop 0
	v_pk_fma_f32 v[96:97], v[90:91], v[96:97], s[64:65] op_sel_hi:[1,1,0]
	s_nop 0
	v_pk_mul_f32 v[90:91], v[90:91], v[96:97]
	s_nop 0
	v_pk_mul_f32 v[90:91], v[92:93], v[90:91]
	s_nop 0
	v_pk_mul_f32 v[92:93], v[88:89], v[90:91]
	v_pk_fma_f32 v[88:89], v[88:89], v[90:91], v[88:89] neg_lo:[1,0,0] neg_hi:[1,0,0]
	v_mov_b32_e32 v90, 0
	v_cndmask_b32_e64 v89, v89, v93, s[0:1]
	v_cndmask_b32_e32 v88, v88, v92, vcc
	v_pk_mul_f32 v[88:89], v[88:89], v[94:95]
	v_cmp_lt_u32_e64 s[0:1], v9, v187
	v_cvt_pk_bf16_f32 v87, v88, v89
	global_store_dwordx4 v[172:173], v[84:87], off offset:1536 nt
	s_and_b64 s[6:7], s[0:1], s[40:41]
	v_mov_b32_e32 v88, 0
	v_mov_b32_e32 v84, 0
	v_mov_b32_e32 v89, 0
	v_mov_b32_e32 v91, 0
	s_and_saveexec_b64 s[66:67], s[6:7]
	s_cbranch_execz .LBB0_733
	v_add_co_u32_e32 v86, vcc, 0x13a59000, v124
	s_nop 1
	v_addc_co_u32_e32 v87, vcc, 0, v125, vcc

; __device__ void phase_conv(const Params& p, int l, int nrows) {
;     ...
;         for (int i = 0; i < 16; ++i) {
;             const bf16_t* np = gp + (size_t)(i + 1) * FF;
;             const bool v = (c0 + i + 1) < W;
;             R[0] = (v && up) ? *(const u32x4*)(np - (size_t)64 * FF) : zero; R[1] = v ? *(const u32x4*)np : zero; R[2] = (v && dn) ? *(const u32x4*)(np + (size_t)64 * FF) : zero;
;             float acc[8];
; #pragma unroll
;             for (int j = 0; j < 8; ++j) acc[j] = bias[j];
.LBB0_737:
	s_or_b64 exec, exec, s[66:67]
	v_add_co_u32_e32 v172, vcc, 0x7faf000, v124
	v_pk_mul_f32 v[140:141], v[12:13], v[148:149]
	s_nop 0
	v_addc_co_u32_e32 v173, vcc, 0, v125, vcc
	v_pk_fma_f32 v[10:11], v[4:5], v[10:11], v[140:141]
	s_waitcnt vmcnt(1)
	v_mov_b64_e32 v[88:89], v[200:201]
	v_mov_b64_e32 v[90:91], v[202:203]
	v_mov_b64_e32 v[84:85], v[204:205]
	v_mov_b64_e32 v[86:87], v[206:207]
	v_mov_b64_e32 v[92:93], v[208:209]
	v_mov_b64_e32 v[94:95], v[210:211]
	v_mov_b64_e32 v[96:97], v[196:197]
	v_mov_b64_e32 v[98:99], v[198:199]
	v_add_u32_e32 v214, -4, v188
	v_cmp_lt_u32_e64 s[98:99], v214, v187
	s_add_u32 s100, s20, 0x7fb1200
	s_addc_u32 s101, s21, 0
	global_load_dwordx4 v[196:199], v192, s[100:101] nt
	v_mov_b32_e32 v200, 0
	v_mov_b32_e32 v201, 0
	v_mov_b32_e32 v202, 0
	v_mov_b32_e32 v203, 0
	v_mov_b32_e32 v204, 0
	v_mov_b32_e32 v205, 0
	v_mov_b32_e32 v206, 0
	v_mov_b32_e32 v207, 0
	v_mov_b32_e32 v208, 0
	v_mov_b32_e32 v209, 0
	v_mov_b32_e32 v210, 0
	v_mov_b32_e32 v211, 0
	s_add_u32 s10, s20, 0x13ab2800
	s_addc_u32 s11, s21, 0
	s_and_saveexec_b64 s[22:23], s[98:99]
	global_load_dwordx4 v[204:207], v192, s[10:11]
	s_add_u32 s100, s20, 0x13a5a800
	s_addc_u32 s101, s21, 0
	s_and_b64 exec, exec, s[40:41]
	global_load_dwordx4 v[200:203], v192, s[100:101]
	s_add_u32 s10, s20, 0x13b0a800
	s_addc_u32 s11, s21, 0
	s_and_b64 exec, s[22:23], s[98:99]
	s_and_b64 exec, exec, s[42:43]
	global_load_dwordx4 v[208:211], v192, s[10:11]
	s_mov_b64 exec, s[22:23]
	v_lshlrev_b32_e32 v152, 16, v88
	v_and_b32_e32 v153, 0xffff0000, v88
	v_pk_mul_f32 v[106:107], v[28:29], v[106:107]
	v_pk_fma_f32 v[10:11], v[20:21], v[152:153], v[10:11]
	v_pk_fma_f32 v[106:107], v[36:37], v[164:165], v[106:107]
	v_lshlrev_b32_e32 v156, 16, v84
	v_and_b32_e32 v157, 0xffff0000, v84
	v_pk_add_f32 v[10:11], v[80:81], v[10:11]
	v_pk_fma_f32 v[106:107], v[44:45], v[156:157], v[106:107]
	v_lshlrev_b32_e32 v170, 16, v92
	v_pk_add_f32 v[10:11], v[10:11], v[106:107]
	v_pk_mul_f32 v[106:107], v[52:53], v[126:127]
	v_and_b32_e32 v171, 0xffff0000, v92
	v_pk_fma_f32 v[106:107], v[60:61], v[162:163], v[106:107]
	v_mov_b64_e32 v[126:127], s[90:91]
	v_pk_fma_f32 v[106:107], v[68:69], v[170:171], v[106:107]
	s_nop 0
	v_lshlrev_b32_e32 v150, 16, v96
	v_pk_add_f32 v[10:11], v[10:11], v[106:107]
	v_and_b32_e32 v151, 0xffff0000, v96
	v_fma_f32 v9, |v10|, s80, 1.0
	v_pk_mul_f32 v[140:141], v[10:11], v[10:11]
	v_rcp_f32_e32 v106, v9
	v_mul_f32_e32 v9, 0xbf38aa3b, v140
	v_exp_f32_e32 v140, v9
	v_fma_f32 v9, |v11|, s80, 1.0
	v_rcp_f32_e32 v107, v9
	v_mul_f32_e32 v9, 0xbf38aa3b, v141
	v_exp_f32_e32 v141, v9
	v_cmp_gt_f32_e32 vcc, 0, v10
	v_pk_fma_f32 v[174:175], v[106:107], s[68:69], v[126:127] op_sel_hi:[1,0,0]
	v_cmp_gt_f32_e64 s[0:1], 0, v11
	v_pk_fma_f32 v[174:175], v[106:107], v[174:175], s[44:45] op_sel_hi:[1,1,0]
	v_lshlrev_b32_e32 v96, 16, v97
	v_pk_fma_f32 v[174:175], v[106:107], v[174:175], s[84:85] op_sel_hi:[1,1,0]
	v_and_b32_e32 v97, 0xffff0000, v97
	v_pk_fma_f32 v[174:175], v[106:107], v[174:175], s[64:65] op_sel_hi:[1,1,0]
	s_nop 0
	v_pk_mul_f32 v[106:107], v[106:107], v[174:175]
	s_nop 0
	v_pk_mul_f32 v[106:107], v[140:141], v[106:107]
	s_nop 0
	v_pk_mul_f32 v[140:141], v[10:11], v[106:107]
	v_pk_fma_f32 v[10:11], v[10:11], v[106:107], v[10:11] neg_lo:[1,0,0] neg_hi:[1,0,0]
	s_nop 0
	v_cndmask_b32_e64 v11, v11, v141, s[0:1]
	v_cndmask_b32_e32 v10, v10, v140, vcc
	v_pk_mul_f32 v[10:11], v[10:11], v[150:151]
	v_lshlrev_b32_e32 v150, 16, v89
	v_cvt_pk_bf16_f32 v84, v10, v11
	v_pk_mul_f32 v[10:11], v[14:15], v[154:155]
	v_and_b32_e32 v151, 0xffff0000, v89
	v_pk_fma_f32 v[10:11], v[6:7], v[128:129], v[10:11]
	v_pk_mul_f32 v[88:89], v[30:31], v[168:169]
	v_pk_fma_f32 v[10:11], v[22:23], v[150:151], v[10:11]
	v_pk_fma_f32 v[88:89], v[38:39], v[160:161], v[88:89]
	v_lshlrev_b32_e32 v168, 16, v85
	v_and_b32_e32 v169, 0xffff0000, v85
	v_pk_add_f32 v[10:11], v[82:83], v[10:11]
	v_pk_fma_f32 v[88:89], v[46:47], v[168:169], v[88:89]
	v_lshlrev_b32_e32 v140, 16, v86
	v_pk_add_f32 v[10:11], v[10:11], v[88:89]
	v_pk_mul_f32 v[88:89], v[54:55], v[166:167]
	v_lshlrev_b32_e32 v166, 16, v93
	v_pk_fma_f32 v[88:89], v[62:63], v[158:159], v[88:89]
	v_and_b32_e32 v167, 0xffff0000, v93
	v_pk_fma_f32 v[88:89], v[70:71], v[166:167], v[88:89]
	v_and_b32_e32 v141, 0xffff0000, v86
	v_pk_add_f32 v[10:11], v[10:11], v[88:89]
	v_lshlrev_b32_e32 v128, 16, v94
	v_fma_f32 v9, |v10|, s80, 1.0
	v_pk_mul_f32 v[92:93], v[10:11], v[10:11]
	v_rcp_f32_e32 v88, v9
	v_mul_f32_e32 v9, 0xbf38aa3b, v92
	v_exp_f32_e32 v92, v9
	v_fma_f32 v9, |v11|, s80, 1.0
	v_rcp_f32_e32 v89, v9
	v_mul_f32_e32 v9, 0xbf38aa3b, v93
	v_exp_f32_e32 v93, v9
	v_cmp_gt_f32_e32 vcc, 0, v10
	v_pk_fma_f32 v[106:107], v[88:89], s[68:69], v[126:127] op_sel_hi:[1,0,0]
	v_cmp_gt_f32_e64 s[0:1], 0, v11
; __device__ __forceinline__ unsigned pk_bf16(float a, float b) { f32x2 v = {a, b}; bf2_t r = __builtin_convertvector(v, bf2_t); return __builtin_bit_cast(unsigned, r); }
; __device__ __forceinline__ float bf_lo(unsigned u) { return __uint_as_float(u << 16); }
; __device__ __forceinline__ float bf_hi(unsigned u) { return __uint_as_float(u & 0xffff0000u); }
; __device__ void phase_conv(const Params& p, int l, int nrows) {
;     ...
; #pragma unroll
;             for (int rr = 0; rr < 3; ++rr) {
; #pragma unroll
;                 for (int j = 0; j < 4; ++j) {
;                     acc[2 * j] += bf_lo(L[rr][j]) * tp[rr * 3 + 0][2 * j] + bf_lo(M[rr][j]) * tp[rr * 3 + 1][2 * j] + bf_lo(R[rr][j]) * tp[rr * 3 + 2][2 * j];
;                     acc[2 * j + 1] += bf_hi(L[rr][j]) * tp[rr * 3 + 0][2 * j + 1] + bf_hi(M[rr][j]) * tp[rr * 3 + 1][2 * j + 1] + bf_hi(R[rr][j]) * tp[rr * 3 + 2][2 * j + 1];
;                 }
;             }
;             bf16_t* ap = Aup + (size_t)(tok0 + i) * FF + f0;
;             const u32x4 av = __builtin_nontemporal_load((const u32x4*)ap);
;             u32x4 wv;
; #pragma unroll
;             for (int j = 0; j < 4; ++j) wv[j] = pk_bf16(bf_lo(av[j]) * gelu_f(acc[2 * j]), bf_hi(av[j]) * gelu_f(acc[2 * j + 1]));
;             *(u32x4*)ap = wv;
; #pragma unroll
;             for (int rr = 0; rr < 3; ++rr) { L[rr] = M[rr]; M[rr] = R[rr]; }
;         }
	v_pk_fma_f32 v[106:107], v[88:89], v[106:107], s[44:45] op_sel_hi:[1,1,0]
	v_and_b32_e32 v129, 0xffff0000, v94
	v_pk_fma_f32 v[106:107], v[88:89], v[106:107], s[84:85] op_sel_hi:[1,1,0]
	v_lshlrev_b32_e32 v94, 16, v99
	v_pk_fma_f32 v[106:107], v[88:89], v[106:107], s[64:65] op_sel_hi:[1,1,0]
	s_nop 0
	v_pk_mul_f32 v[88:89], v[88:89], v[106:107]
	v_lshlrev_b32_e32 v106, 16, v95
	v_pk_mul_f32 v[88:89], v[92:93], v[88:89]
	v_and_b32_e32 v107, 0xffff0000, v95
	v_pk_mul_f32 v[92:93], v[10:11], v[88:89]
	v_pk_fma_f32 v[10:11], v[10:11], v[88:89], v[10:11] neg_lo:[1,0,0] neg_hi:[1,0,0]
	v_pk_mul_f32 v[88:89], v[32:33], v[104:105]
	v_cndmask_b32_e64 v11, v11, v93, s[0:1]
	v_cndmask_b32_e32 v10, v10, v92, vcc
	v_pk_mul_f32 v[10:11], v[10:11], v[96:97]
	v_pk_fma_f32 v[88:89], v[40:41], v[144:145], v[88:89]
	v_cvt_pk_bf16_f32 v85, v10, v11
	v_pk_mul_f32 v[10:11], v[16:17], v[114:115]
	v_pk_fma_f32 v[88:89], v[48:49], v[140:141], v[88:89]
	v_pk_fma_f32 v[10:11], v[0:1], v[100:101], v[10:11]
	v_lshlrev_b32_e32 v100, 16, v90
	v_and_b32_e32 v101, 0xffff0000, v90
	v_pk_fma_f32 v[10:11], v[24:25], v[100:101], v[10:11]
	v_lshlrev_b32_e32 v96, 16, v98
	v_pk_add_f32 v[10:11], v[76:77], v[10:11]
	v_and_b32_e32 v97, 0xffff0000, v98
	v_pk_add_f32 v[10:11], v[10:11], v[88:89]
	v_pk_mul_f32 v[88:89], v[56:57], v[108:109]
	v_lshlrev_b32_e32 v108, 16, v87
	v_pk_fma_f32 v[88:89], v[64:65], v[118:119], v[88:89]
	v_and_b32_e32 v109, 0xffff0000, v87
	v_pk_fma_f32 v[88:89], v[72:73], v[128:129], v[88:89]
	v_and_b32_e32 v95, 0xffff0000, v99
	v_pk_add_f32 v[10:11], v[10:11], v[88:89]
	s_nop 0
	v_fma_f32 v9, |v10|, s80, 1.0
	v_pk_mul_f32 v[92:93], v[10:11], v[10:11]
	v_rcp_f32_e32 v88, v9
	v_mul_f32_e32 v9, 0xbf38aa3b, v92
	v_exp_f32_e32 v92, v9
	v_fma_f32 v9, |v11|, s80, 1.0
	v_rcp_f32_e32 v89, v9
	v_mul_f32_e32 v9, 0xbf38aa3b, v93
	v_exp_f32_e32 v93, v9
	v_cmp_gt_f32_e32 vcc, 0, v10
	v_pk_fma_f32 v[104:105], v[88:89], s[68:69], v[126:127] op_sel_hi:[1,0,0]
	v_cmp_gt_f32_e64 s[0:1], 0, v11
	v_pk_fma_f32 v[104:105], v[88:89], v[104:105], s[44:45] op_sel_hi:[1,1,0]
	s_nop 0
	v_pk_fma_f32 v[104:105], v[88:89], v[104:105], s[84:85] op_sel_hi:[1,1,0]
	s_nop 0
	v_pk_fma_f32 v[104:105], v[88:89], v[104:105], s[64:65] op_sel_hi:[1,1,0]
	s_nop 0
	v_pk_mul_f32 v[88:89], v[88:89], v[104:105]
	s_nop 0
	v_pk_mul_f32 v[88:89], v[92:93], v[88:89]
	s_nop 0
	v_pk_mul_f32 v[92:93], v[10:11], v[88:89]
	v_pk_fma_f32 v[10:11], v[10:11], v[88:89], v[10:11] neg_lo:[1,0,0] neg_hi:[1,0,0]
	s_nop 0
	v_cndmask_b32_e64 v11, v11, v93, s[0:1]
	v_cndmask_b32_e32 v10, v10, v92, vcc
	v_pk_mul_f32 v[10:11], v[10:11], v[96:97]
	s_nop 0
	v_cvt_pk_bf16_f32 v86, v10, v11
	v_pk_mul_f32 v[10:11], v[18:19], v[110:111]
	s_nop 0
	v_pk_fma_f32 v[88:89], v[2:3], v[112:113], v[10:11]
	v_lshlrev_b32_e32 v10, 16, v91
	v_and_b32_e32 v11, 0xffff0000, v91
	v_pk_mul_f32 v[90:91], v[34:35], v[102:103]
	v_pk_fma_f32 v[88:89], v[26:27], v[10:11], v[88:89]
	v_pk_fma_f32 v[90:91], v[42:43], v[116:117], v[90:91]
	v_pk_add_f32 v[88:89], v[78:79], v[88:89]
	v_pk_fma_f32 v[90:91], v[50:51], v[108:109], v[90:91]
	s_nop 0
	v_pk_add_f32 v[88:89], v[88:89], v[90:91]
	v_pk_mul_f32 v[90:91], v[58:59], v[146:147]
	s_nop 0
	v_pk_fma_f32 v[90:91], v[66:67], v[142:143], v[90:91]
	s_nop 0
	v_pk_fma_f32 v[90:91], v[74:75], v[106:107], v[90:91]
	s_nop 0
	v_pk_add_f32 v[88:89], v[88:89], v[90:91]
	s_nop 0
	v_fma_f32 v9, |v88|, s80, 1.0
	v_pk_mul_f32 v[92:93], v[88:89], v[88:89]
	v_rcp_f32_e32 v90, v9
	v_mul_f32_e32 v9, 0xbf38aa3b, v92
	v_exp_f32_e32 v92, v9
	v_fma_f32 v9, |v89|, s80, 1.0
	v_rcp_f32_e32 v91, v9
	v_mul_f32_e32 v9, 0xbf38aa3b, v93
	v_exp_f32_e32 v93, v9
	v_cmp_gt_f32_e32 vcc, 0, v88
	v_pk_fma_f32 v[96:97], v[90:91], s[68:69], v[126:127] op_sel_hi:[1,0,0]
	v_cmp_gt_f32_e64 s[0:1], 0, v89
	v_pk_fma_f32 v[96:97], v[90:91], v[96:97], s[44:45] op_sel_hi:[1,1,0]
	v_add_u32_e32 v9, -4, v188
	v_pk_fma_f32 v[96:97], v[90:91], v[96:97], s[84:85] op_sel_hi:[1,1,0]
	s_nop 0
	v_pk_fma_f32 v[96:97], v[90:91], v[96:97], s[64:65] op_sel_hi:[1,1,0]
	s_nop 0
	v_pk_mul_f32 v[90:91], v[90:91], v[96:97]
	s_nop 0
	v_pk_mul_f32 v[90:91], v[92:93], v[90:91]
	s_nop 0
	v_pk_mul_f32 v[92:93], v[88:89], v[90:91]
	v_pk_fma_f32 v[88:89], v[88:89], v[90:91], v[88:89] neg_lo:[1,0,0] neg_hi:[1,0,0]
	v_mov_b32_e32 v90, 0
	v_cndmask_b32_e64 v89, v89, v93, s[0:1]
	v_cndmask_b32_e32 v88, v88, v92, vcc
	v_pk_mul_f32 v[88:89], v[88:89], v[94:95]
	v_cmp_lt_u32_e64 s[0:1], v9, v187
	v_cvt_pk_bf16_f32 v87, v88, v89
	global_store_dwordx4 v[172:173], v[84:87], off offset:3072 nt
	s_and_b64 s[6:7], s[0:1], s[40:41]
	v_mov_b32_e32 v88, 0
	v_mov_b32_e32 v84, 0
	v_mov_b32_e32 v89, 0
	v_mov_b32_e32 v91, 0
	s_and_saveexec_b64 s[66:67], s[6:7]
	s_cbranch_execz .LBB0_739
	v_add_co_u32_e32 v86, vcc, 0x13a5a000, v124
	s_nop 1
	v_addc_co_u32_e32 v87, vcc, 0, v125, vcc

; __device__ void phase_conv(const Params& p, int l, int nrows) {
;     ...
;         for (int i = 0; i < 16; ++i) {
;             const bf16_t* np = gp + (size_t)(i + 1) * FF;
;             const bool v = (c0 + i + 1) < W;
;             R[0] = (v && up) ? *(const u32x4*)(np - (size_t)64 * FF) : zero; R[1] = v ? *(const u32x4*)np : zero; R[2] = (v && dn) ? *(const u32x4*)(np + (size_t)64 * FF) : zero;
;             float acc[8];
; #pragma unroll
;             for (int j = 0; j < 8; ++j) acc[j] = bias[j];
.LBB0_743:
	s_or_b64 exec, exec, s[66:67]
	v_add_co_u32_e32 v112, vcc, 0x7fb1000, v124
	v_pk_mul_f32 v[102:103], v[12:13], v[152:153]
	s_nop 0
	v_addc_co_u32_e32 v113, vcc, 0, v125, vcc
	v_pk_fma_f32 v[102:103], v[4:5], v[148:149], v[102:103]
	s_waitcnt vmcnt(1)
	v_mov_b64_e32 v[88:89], v[200:201]
	v_mov_b64_e32 v[90:91], v[202:203]
	v_mov_b64_e32 v[84:85], v[204:205]
	v_mov_b64_e32 v[86:87], v[206:207]
	v_mov_b64_e32 v[92:93], v[208:209]
	v_mov_b64_e32 v[94:95], v[210:211]
	v_mov_b64_e32 v[96:97], v[196:197]
	v_mov_b64_e32 v[98:99], v[198:199]
	v_add_u32_e32 v214, -3, v188
	v_cmp_lt_u32_e64 s[98:99], v214, v187
	s_add_u32 s100, s20, 0x7fb2800
	s_addc_u32 s101, s21, 0
	global_load_dwordx4 v[196:199], v192, s[100:101] nt
	v_mov_b32_e32 v200, 0
	v_mov_b32_e32 v201, 0
	v_mov_b32_e32 v202, 0
	v_mov_b32_e32 v203, 0
	v_mov_b32_e32 v204, 0
	v_mov_b32_e32 v205, 0
	v_mov_b32_e32 v206, 0
	v_mov_b32_e32 v207, 0
	v_mov_b32_e32 v208, 0
	v_mov_b32_e32 v209, 0
	v_mov_b32_e32 v210, 0
	v_mov_b32_e32 v211, 0
	s_add_u32 s10, s20, 0x13ab3e00
	s_addc_u32 s11, s21, 0
	s_and_saveexec_b64 s[22:23], s[98:99]
	global_load_dwordx4 v[204:207], v192, s[10:11]
	s_add_u32 s100, s20, 0x13a5be00
	s_addc_u32 s101, s21, 0
	s_and_b64 exec, exec, s[40:41]
	global_load_dwordx4 v[200:203], v192, s[100:101]
	s_add_u32 s10, s20, 0x13b0be00
	s_addc_u32 s11, s21, 0
	s_and_b64 exec, s[22:23], s[98:99]
	s_and_b64 exec, exec, s[42:43]
	global_load_dwordx4 v[208:211], v192, s[10:11]
	s_mov_b64 exec, s[22:23]
	v_lshlrev_b32_e32 v148, 16, v88
	v_and_b32_e32 v149, 0xffff0000, v88
	v_pk_mul_f32 v[104:105], v[28:29], v[164:165]
	v_pk_fma_f32 v[102:103], v[20:21], v[148:149], v[102:103]
	v_pk_fma_f32 v[104:105], v[36:37], v[156:157], v[104:105]
	v_lshlrev_b32_e32 v164, 16, v84
	v_and_b32_e32 v165, 0xffff0000, v84
	v_pk_add_f32 v[102:103], v[80:81], v[102:103]
	v_pk_fma_f32 v[104:105], v[44:45], v[164:165], v[104:105]
	v_mov_b64_e32 v[172:173], s[90:91]
	v_pk_add_f32 v[102:103], v[102:103], v[104:105]
	v_pk_mul_f32 v[104:105], v[52:53], v[162:163]
	v_lshlrev_b32_e32 v162, 16, v92
	v_pk_fma_f32 v[104:105], v[60:61], v[170:171], v[104:105]
	v_and_b32_e32 v163, 0xffff0000, v92
	v_pk_fma_f32 v[104:105], v[68:69], v[162:163], v[104:105]
	s_nop 0
	v_lshlrev_b32_e32 v146, 16, v96
	v_pk_add_f32 v[102:103], v[102:103], v[104:105]
	v_and_b32_e32 v147, 0xffff0000, v96
	v_fma_f32 v9, |v102|, s80, 1.0
	v_pk_mul_f32 v[126:127], v[102:103], v[102:103]
	v_rcp_f32_e32 v104, v9
	v_mul_f32_e32 v9, 0xbf38aa3b, v126
	v_exp_f32_e32 v126, v9
	v_fma_f32 v9, |v103|, s80, 1.0
	v_rcp_f32_e32 v105, v9
	v_mul_f32_e32 v9, 0xbf38aa3b, v127
	v_exp_f32_e32 v127, v9
	v_cmp_gt_f32_e32 vcc, 0, v102
	v_pk_fma_f32 v[174:175], v[104:105], s[68:69], v[172:173] op_sel_hi:[1,0,0]
	v_cmp_gt_f32_e64 s[0:1], 0, v103
	v_pk_fma_f32 v[174:175], v[104:105], v[174:175], s[44:45] op_sel_hi:[1,1,0]
	s_nop 0
	v_pk_fma_f32 v[174:175], v[104:105], v[174:175], s[84:85] op_sel_hi:[1,1,0]
	s_nop 0
	v_pk_fma_f32 v[174:175], v[104:105], v[174:175], s[64:65] op_sel_hi:[1,1,0]
	s_nop 0
	v_pk_mul_f32 v[104:105], v[104:105], v[174:175]
	s_nop 0
	v_pk_mul_f32 v[104:105], v[126:127], v[104:105]
	s_nop 0
	v_pk_mul_f32 v[126:127], v[102:103], v[104:105]
	v_pk_fma_f32 v[102:103], v[102:103], v[104:105], v[102:103] neg_lo:[1,0,0] neg_hi:[1,0,0]
	v_lshlrev_b32_e32 v104, 16, v97
	v_cndmask_b32_e64 v103, v103, v127, s[0:1]
	v_cndmask_b32_e32 v102, v102, v126, vcc
	v_pk_mul_f32 v[102:103], v[102:103], v[146:147]
	v_lshlrev_b32_e32 v146, 16, v89
	v_cvt_pk_bf16_f32 v84, v102, v103
	v_pk_mul_f32 v[102:103], v[14:15], v[150:151]
	v_and_b32_e32 v147, 0xffff0000, v89
	v_pk_fma_f32 v[102:103], v[6:7], v[154:155], v[102:103]
	v_and_b32_e32 v105, 0xffff0000, v97
	v_pk_fma_f32 v[88:89], v[22:23], v[146:147], v[102:103]
	v_pk_mul_f32 v[102:103], v[30:31], v[160:161]
	v_lshlrev_b32_e32 v160, 16, v85
	v_pk_fma_f32 v[102:103], v[38:39], v[168:169], v[102:103]
	v_and_b32_e32 v161, 0xffff0000, v85
	v_pk_add_f32 v[88:89], v[82:83], v[88:89]
	v_pk_fma_f32 v[102:103], v[46:47], v[160:161], v[102:103]
	s_nop 0
	v_pk_add_f32 v[88:89], v[88:89], v[102:103]
	v_pk_mul_f32 v[102:103], v[54:55], v[158:159]
	v_lshlrev_b32_e32 v158, 16, v93
	v_pk_fma_f32 v[102:103], v[62:63], v[166:167], v[102:103]
	v_and_b32_e32 v159, 0xffff0000, v93
	v_pk_fma_f32 v[92:93], v[70:71], v[158:159], v[102:103]
	s_nop 0
	v_pk_add_f32 v[88:89], v[88:89], v[92:93]
	s_nop 0
	v_fma_f32 v9, |v88|, s80, 1.0
	v_pk_mul_f32 v[102:103], v[88:89], v[88:89]
	v_rcp_f32_e32 v92, v9
	v_mul_f32_e32 v9, 0xbf38aa3b, v102
	v_exp_f32_e32 v96, v9
	v_fma_f32 v9, |v89|, s80, 1.0
	v_rcp_f32_e32 v93, v9
	v_mul_f32_e32 v9, 0xbf38aa3b, v103
	v_exp_f32_e32 v97, v9
	v_cmp_gt_f32_e32 vcc, 0, v88
	v_pk_fma_f32 v[126:127], v[92:93], s[68:69], v[172:173] op_sel_hi:[1,0,0]
	v_cmp_gt_f32_e64 s[0:1], 0, v89
	v_pk_fma_f32 v[126:127], v[92:93], v[126:127], s[44:45] op_sel_hi:[1,1,0]
; __device__ __forceinline__ unsigned pk_bf16(float a, float b) { f32x2 v = {a, b}; bf2_t r = __builtin_convertvector(v, bf2_t); return __builtin_bit_cast(unsigned, r); }
; __device__ __forceinline__ float bf_lo(unsigned u) { return __uint_as_float(u << 16); }
; __device__ __forceinline__ float bf_hi(unsigned u) { return __uint_as_float(u & 0xffff0000u); }
; __device__ void phase_conv(const Params& p, int l, int nrows) {
;     ...
; #pragma unroll
;             for (int rr = 0; rr < 3; ++rr) {
; #pragma unroll
;                 for (int j = 0; j < 4; ++j) {
;                     acc[2 * j] += bf_lo(L[rr][j]) * tp[rr * 3 + 0][2 * j] + bf_lo(M[rr][j]) * tp[rr * 3 + 1][2 * j] + bf_lo(R[rr][j]) * tp[rr * 3 + 2][2 * j];
;                     acc[2 * j + 1] += bf_hi(L[rr][j]) * tp[rr * 3 + 0][2 * j + 1] + bf_hi(M[rr][j]) * tp[rr * 3 + 1][2 * j + 1] + bf_hi(R[rr][j]) * tp[rr * 3 + 2][2 * j + 1];
;                 }
;             }
;             bf16_t* ap = Aup + (size_t)(tok0 + i) * FF + f0;
;             const u32x4 av = __builtin_nontemporal_load((const u32x4*)ap);
;             u32x4 wv;
; #pragma unroll
;             for (int j = 0; j < 4; ++j) wv[j] = pk_bf16(bf_lo(av[j]) * gelu_f(acc[2 * j]), bf_hi(av[j]) * gelu_f(acc[2 * j + 1]));
;             *(u32x4*)ap = wv;
; #pragma unroll
;             for (int rr = 0; rr < 3; ++rr) { L[rr] = M[rr]; M[rr] = R[rr]; }
;         }
	v_lshlrev_b32_e32 v102, 16, v98
	v_pk_fma_f32 v[126:127], v[92:93], v[126:127], s[84:85] op_sel_hi:[1,1,0]
	v_and_b32_e32 v103, 0xffff0000, v98
	v_pk_fma_f32 v[126:127], v[92:93], v[126:127], s[64:65] op_sel_hi:[1,1,0]
	s_nop 0
	v_pk_mul_f32 v[92:93], v[92:93], v[126:127]
	v_lshlrev_b32_e32 v126, 16, v86
	v_pk_mul_f32 v[92:93], v[96:97], v[92:93]
	v_and_b32_e32 v127, 0xffff0000, v86
	v_pk_mul_f32 v[96:97], v[88:89], v[92:93]
	v_pk_fma_f32 v[88:89], v[88:89], v[92:93], v[88:89] neg_lo:[1,0,0] neg_hi:[1,0,0]
	v_pk_mul_f32 v[92:93], v[32:33], v[144:145]
	v_cndmask_b32_e64 v89, v89, v97, s[0:1]
	v_cndmask_b32_e32 v88, v88, v96, vcc
	v_pk_mul_f32 v[88:89], v[88:89], v[104:105]
	v_lshlrev_b32_e32 v104, 16, v90
	v_cvt_pk_bf16_f32 v85, v88, v89
	v_pk_mul_f32 v[88:89], v[16:17], v[100:101]
	v_and_b32_e32 v105, 0xffff0000, v90
	v_pk_fma_f32 v[88:89], v[0:1], v[114:115], v[88:89]
	v_pk_fma_f32 v[92:93], v[40:41], v[140:141], v[92:93]
	v_pk_fma_f32 v[88:89], v[24:25], v[104:105], v[88:89]
	v_pk_fma_f32 v[92:93], v[48:49], v[126:127], v[92:93]
	v_pk_add_f32 v[88:89], v[76:77], v[88:89]
	s_nop 0
	v_pk_add_f32 v[88:89], v[88:89], v[92:93]
	v_pk_mul_f32 v[92:93], v[56:57], v[118:119]
	v_lshlrev_b32_e32 v118, 16, v94
	v_pk_fma_f32 v[92:93], v[64:65], v[128:129], v[92:93]
	v_and_b32_e32 v119, 0xffff0000, v94
	v_pk_fma_f32 v[92:93], v[72:73], v[118:119], v[92:93]
	v_lshlrev_b32_e32 v94, 16, v99
	v_pk_add_f32 v[88:89], v[88:89], v[92:93]
	s_nop 0
	v_fma_f32 v9, |v88|, s80, 1.0
	v_pk_mul_f32 v[96:97], v[88:89], v[88:89]
	v_rcp_f32_e32 v92, v9
	v_mul_f32_e32 v9, 0xbf38aa3b, v96
	v_exp_f32_e32 v96, v9
	v_fma_f32 v9, |v89|, s80, 1.0
	v_rcp_f32_e32 v93, v9
	v_mul_f32_e32 v9, 0xbf38aa3b, v97
	v_exp_f32_e32 v97, v9
	v_cmp_gt_f32_e32 vcc, 0, v88
	v_pk_fma_f32 v[114:115], v[92:93], s[68:69], v[172:173] op_sel_hi:[1,0,0]
	v_cmp_gt_f32_e64 s[0:1], 0, v89
	v_pk_fma_f32 v[114:115], v[92:93], v[114:115], s[44:45] op_sel_hi:[1,1,0]
	s_nop 0
	v_pk_fma_f32 v[114:115], v[92:93], v[114:115], s[84:85] op_sel_hi:[1,1,0]
	s_nop 0
	v_pk_fma_f32 v[114:115], v[92:93], v[114:115], s[64:65] op_sel_hi:[1,1,0]
	s_nop 0
	v_pk_mul_f32 v[92:93], v[92:93], v[114:115]
	v_lshlrev_b32_e32 v114, 16, v95
	v_pk_mul_f32 v[92:93], v[96:97], v[92:93]
	v_and_b32_e32 v115, 0xffff0000, v95
	v_pk_mul_f32 v[96:97], v[88:89], v[92:93]
	v_pk_fma_f32 v[88:89], v[88:89], v[92:93], v[88:89] neg_lo:[1,0,0] neg_hi:[1,0,0]
	v_and_b32_e32 v95, 0xffff0000, v99
	v_cndmask_b32_e64 v89, v89, v97, s[0:1]
	v_cndmask_b32_e32 v88, v88, v96, vcc
	v_pk_mul_f32 v[88:89], v[88:89], v[102:103]
	v_lshlrev_b32_e32 v102, 16, v91
	v_cvt_pk_bf16_f32 v86, v88, v89
	v_pk_mul_f32 v[88:89], v[18:19], v[10:11]
	v_and_b32_e32 v103, 0xffff0000, v91
	v_pk_fma_f32 v[88:89], v[2:3], v[110:111], v[88:89]
	v_pk_mul_f32 v[90:91], v[34:35], v[116:117]
	v_pk_fma_f32 v[88:89], v[26:27], v[102:103], v[88:89]
	v_pk_fma_f32 v[90:91], v[42:43], v[108:109], v[90:91]
	v_lshlrev_b32_e32 v116, 16, v87
	v_and_b32_e32 v117, 0xffff0000, v87
	v_pk_add_f32 v[88:89], v[78:79], v[88:89]
	v_pk_fma_f32 v[90:91], v[50:51], v[116:117], v[90:91]
	s_nop 0
	v_pk_add_f32 v[88:89], v[88:89], v[90:91]
	v_pk_mul_f32 v[90:91], v[58:59], v[142:143]
	s_nop 0
	v_pk_fma_f32 v[90:91], v[66:67], v[106:107], v[90:91]
	s_nop 0
	v_pk_fma_f32 v[90:91], v[74:75], v[114:115], v[90:91]
	s_nop 0
	v_pk_add_f32 v[88:89], v[88:89], v[90:91]
	s_nop 0
	v_fma_f32 v9, |v88|, s80, 1.0
	v_pk_mul_f32 v[92:93], v[88:89], v[88:89]
	v_rcp_f32_e32 v90, v9
	v_mul_f32_e32 v9, 0xbf38aa3b, v92
	v_exp_f32_e32 v92, v9
	v_fma_f32 v9, |v89|, s80, 1.0
	v_rcp_f32_e32 v91, v9
	v_mul_f32_e32 v9, 0xbf38aa3b, v93
	v_exp_f32_e32 v93, v9
	v_cmp_gt_f32_e32 vcc, 0, v88
	v_pk_fma_f32 v[96:97], v[90:91], s[68:69], v[172:173] op_sel_hi:[1,0,0]
	v_cmp_gt_f32_e64 s[0:1], 0, v89
	v_pk_fma_f32 v[96:97], v[90:91], v[96:97], s[44:45] op_sel_hi:[1,1,0]
	v_add_u32_e32 v9, -3, v188
	v_pk_fma_f32 v[96:97], v[90:91], v[96:97], s[84:85] op_sel_hi:[1,1,0]
	s_nop 0
	v_pk_fma_f32 v[96:97], v[90:91], v[96:97], s[64:65] op_sel_hi:[1,1,0]
	s_nop 0
	v_pk_mul_f32 v[90:91], v[90:91], v[96:97]
	s_nop 0
	v_pk_mul_f32 v[90:91], v[92:93], v[90:91]
	s_nop 0
	v_pk_mul_f32 v[92:93], v[88:89], v[90:91]
	v_pk_fma_f32 v[88:89], v[88:89], v[90:91], v[88:89] neg_lo:[1,0,0] neg_hi:[1,0,0]
	v_mov_b32_e32 v90, 0
	v_cndmask_b32_e64 v89, v89, v93, s[0:1]
	v_cndmask_b32_e32 v88, v88, v92, vcc
	v_pk_mul_f32 v[88:89], v[88:89], v[94:95]
	v_cmp_lt_u32_e64 s[0:1], v9, v187
	v_cvt_pk_bf16_f32 v87, v88, v89
	global_store_dwordx4 v[112:113], v[84:87], off offset:512 nt
	s_and_b64 s[6:7], s[0:1], s[40:41]
	v_mov_b32_e32 v88, 0
	v_mov_b32_e32 v84, 0
	v_mov_b32_e32 v89, 0
	v_mov_b32_e32 v91, 0
	s_and_saveexec_b64 s[66:67], s[6:7]
	s_cbranch_execz .LBB0_745
	v_add_co_u32_e32 v86, vcc, 0x13a5b000, v124
	s_nop 1
	v_addc_co_u32_e32 v87, vcc, 0, v125, vcc

; __device__ void phase_conv(const Params& p, int l, int nrows) {
;     ...
;         for (int i = 0; i < 16; ++i) {
;             const bf16_t* np = gp + (size_t)(i + 1) * FF;
;             const bool v = (c0 + i + 1) < W;
;             R[0] = (v && up) ? *(const u32x4*)(np - (size_t)64 * FF) : zero; R[1] = v ? *(const u32x4*)np : zero; R[2] = (v && dn) ? *(const u32x4*)(np + (size_t)64 * FF) : zero;
;             float acc[8];
; #pragma unroll
;             for (int j = 0; j < 8; ++j) acc[j] = bias[j];
.LBB0_749:
	s_or_b64 exec, exec, s[66:67]
	v_add_co_u32_e32 v172, vcc, 0x7fb2000, v124
	v_pk_mul_f32 v[110:111], v[12:13], v[148:149]
	s_nop 0
	v_addc_co_u32_e32 v173, vcc, 0, v125, vcc
	v_pk_fma_f32 v[110:111], v[4:5], v[152:153], v[110:111]
	s_waitcnt vmcnt(1)
	v_mov_b64_e32 v[88:89], v[200:201]
	v_mov_b64_e32 v[90:91], v[202:203]
	v_mov_b64_e32 v[84:85], v[204:205]
	v_mov_b64_e32 v[86:87], v[206:207]
	v_mov_b64_e32 v[92:93], v[208:209]
	v_mov_b64_e32 v[94:95], v[210:211]
	v_mov_b64_e32 v[96:97], v[196:197]
	v_mov_b64_e32 v[98:99], v[198:199]
	v_add_u32_e32 v214, -2, v188
	v_cmp_lt_u32_e64 s[98:99], v214, v187
	s_add_u32 s100, s20, 0x7fb3e00
	s_addc_u32 s101, s21, 0
	global_load_dwordx4 v[196:199], v192, s[100:101] nt
	v_mov_b32_e32 v200, 0
	v_mov_b32_e32 v201, 0
	v_mov_b32_e32 v202, 0
	v_mov_b32_e32 v203, 0
	v_mov_b32_e32 v204, 0
	v_mov_b32_e32 v205, 0
	v_mov_b32_e32 v206, 0
	v_mov_b32_e32 v207, 0
	v_mov_b32_e32 v208, 0
	v_mov_b32_e32 v209, 0
	v_mov_b32_e32 v210, 0
	v_mov_b32_e32 v211, 0
	s_add_u32 s10, s20, 0x13ab5400
	s_addc_u32 s11, s21, 0
	s_and_saveexec_b64 s[22:23], s[98:99]
	global_load_dwordx4 v[204:207], v192, s[10:11]
	s_add_u32 s100, s20, 0x13a5d400
	s_addc_u32 s101, s21, 0
	s_and_b64 exec, exec, s[40:41]
	global_load_dwordx4 v[200:203], v192, s[100:101]
	s_add_u32 s10, s20, 0x13b0d400
	s_addc_u32 s11, s21, 0
	s_and_b64 exec, s[22:23], s[98:99]
	s_and_b64 exec, exec, s[42:43]
	global_load_dwordx4 v[208:211], v192, s[10:11]
	s_mov_b64 exec, s[22:23]
	v_lshlrev_b32_e32 v144, 16, v88
	v_and_b32_e32 v145, 0xffff0000, v88
	v_pk_mul_f32 v[112:113], v[28:29], v[156:157]
	v_pk_fma_f32 v[110:111], v[20:21], v[144:145], v[110:111]
	v_pk_fma_f32 v[112:113], v[36:37], v[164:165], v[112:113]
	v_lshlrev_b32_e32 v156, 16, v84
	v_and_b32_e32 v157, 0xffff0000, v84
	v_pk_add_f32 v[110:111], v[80:81], v[110:111]
	v_pk_fma_f32 v[112:113], v[44:45], v[156:157], v[112:113]
	v_lshlrev_b32_e32 v154, 16, v92
	v_pk_add_f32 v[110:111], v[110:111], v[112:113]
	v_pk_mul_f32 v[112:113], v[52:53], v[170:171]
	v_and_b32_e32 v155, 0xffff0000, v92
	v_pk_fma_f32 v[112:113], v[60:61], v[162:163], v[112:113]
	v_mov_b64_e32 v[170:171], s[90:91]
	v_pk_fma_f32 v[112:113], v[68:69], v[154:155], v[112:113]
	s_nop 0
	v_lshlrev_b32_e32 v152, 16, v96
	v_pk_add_f32 v[110:111], v[110:111], v[112:113]
	v_and_b32_e32 v153, 0xffff0000, v96
	v_fma_f32 v9, |v110|, s80, 1.0
	v_pk_mul_f32 v[142:143], v[110:111], v[110:111]
	v_rcp_f32_e32 v112, v9
	v_mul_f32_e32 v9, 0xbf38aa3b, v142
	v_exp_f32_e32 v142, v9
	v_fma_f32 v9, |v111|, s80, 1.0
	v_rcp_f32_e32 v113, v9
	v_mul_f32_e32 v9, 0xbf38aa3b, v143
	v_exp_f32_e32 v143, v9
	v_cmp_gt_f32_e32 vcc, 0, v110
	v_pk_fma_f32 v[174:175], v[112:113], s[68:69], v[170:171] op_sel_hi:[1,0,0]
	v_cmp_gt_f32_e64 s[0:1], 0, v111
	v_pk_fma_f32 v[174:175], v[112:113], v[174:175], s[44:45] op_sel_hi:[1,1,0]
	s_nop 0
	v_pk_fma_f32 v[174:175], v[112:113], v[174:175], s[84:85] op_sel_hi:[1,1,0]
	s_nop 0
	v_pk_fma_f32 v[174:175], v[112:113], v[174:175], s[64:65] op_sel_hi:[1,1,0]
	s_nop 0
	v_pk_mul_f32 v[112:113], v[112:113], v[174:175]
	s_nop 0
	v_pk_mul_f32 v[112:113], v[142:143], v[112:113]
	s_nop 0
	v_pk_mul_f32 v[142:143], v[110:111], v[112:113]
	v_pk_fma_f32 v[110:111], v[110:111], v[112:113], v[110:111] neg_lo:[1,0,0] neg_hi:[1,0,0]
	v_lshlrev_b32_e32 v112, 16, v97
	v_cndmask_b32_e64 v111, v111, v143, s[0:1]
	v_cndmask_b32_e32 v110, v110, v142, vcc
	v_pk_mul_f32 v[110:111], v[110:111], v[152:153]
	v_lshlrev_b32_e32 v142, 16, v89
	v_cvt_pk_bf16_f32 v84, v110, v111
	v_pk_mul_f32 v[110:111], v[14:15], v[146:147]
	v_and_b32_e32 v143, 0xffff0000, v89
	v_pk_fma_f32 v[110:111], v[6:7], v[150:151], v[110:111]
	v_lshlrev_b32_e32 v152, 16, v85
	v_pk_fma_f32 v[88:89], v[22:23], v[142:143], v[110:111]
	v_pk_mul_f32 v[110:111], v[30:31], v[168:169]
	v_and_b32_e32 v153, 0xffff0000, v85
	v_pk_fma_f32 v[110:111], v[38:39], v[160:161], v[110:111]
	v_pk_add_f32 v[88:89], v[82:83], v[88:89]
	v_pk_fma_f32 v[110:111], v[46:47], v[152:153], v[110:111]
	v_lshlrev_b32_e32 v150, 16, v93
	v_pk_add_f32 v[88:89], v[88:89], v[110:111]
	v_pk_mul_f32 v[110:111], v[54:55], v[166:167]
	v_and_b32_e32 v151, 0xffff0000, v93
	v_pk_fma_f32 v[110:111], v[62:63], v[158:159], v[110:111]
	v_and_b32_e32 v113, 0xffff0000, v97
	v_pk_fma_f32 v[92:93], v[70:71], v[150:151], v[110:111]
	s_nop 0
	v_pk_add_f32 v[88:89], v[88:89], v[92:93]
	s_nop 0
	v_fma_f32 v9, |v88|, s80, 1.0
	v_pk_mul_f32 v[110:111], v[88:89], v[88:89]
	v_rcp_f32_e32 v92, v9
	v_mul_f32_e32 v9, 0xbf38aa3b, v110
	v_exp_f32_e32 v96, v9
	v_fma_f32 v9, |v89|, s80, 1.0
	v_rcp_f32_e32 v93, v9
	v_mul_f32_e32 v9, 0xbf38aa3b, v111
	v_exp_f32_e32 v97, v9
	v_cmp_gt_f32_e32 vcc, 0, v88
	v_pk_fma_f32 v[166:167], v[92:93], s[68:69], v[170:171] op_sel_hi:[1,0,0]
	v_cmp_gt_f32_e64 s[0:1], 0, v89
	v_pk_fma_f32 v[166:167], v[92:93], v[166:167], s[44:45] op_sel_hi:[1,1,0]
; __device__ __forceinline__ unsigned pk_bf16(float a, float b) { f32x2 v = {a, b}; bf2_t r = __builtin_convertvector(v, bf2_t); return __builtin_bit_cast(unsigned, r); }
; __device__ __forceinline__ float bf_lo(unsigned u) { return __uint_as_float(u << 16); }
; __device__ __forceinline__ float bf_hi(unsigned u) { return __uint_as_float(u & 0xffff0000u); }
; __device__ void phase_conv(const Params& p, int l, int nrows) {
;     ...
; #pragma unroll
;             for (int rr = 0; rr < 3; ++rr) {
; #pragma unroll
;                 for (int j = 0; j < 4; ++j) {
;                     acc[2 * j] += bf_lo(L[rr][j]) * tp[rr * 3 + 0][2 * j] + bf_lo(M[rr][j]) * tp[rr * 3 + 1][2 * j] + bf_lo(R[rr][j]) * tp[rr * 3 + 2][2 * j];
;                     acc[2 * j + 1] += bf_hi(L[rr][j]) * tp[rr * 3 + 0][2 * j + 1] + bf_hi(M[rr][j]) * tp[rr * 3 + 1][2 * j + 1] + bf_hi(R[rr][j]) * tp[rr * 3 + 2][2 * j + 1];
;                 }
;             }
;             bf16_t* ap = Aup + (size_t)(tok0 + i) * FF + f0;
;             const u32x4 av = __builtin_nontemporal_load((const u32x4*)ap);
;             u32x4 wv;
; #pragma unroll
;             for (int j = 0; j < 4; ++j) wv[j] = pk_bf16(bf_lo(av[j]) * gelu_f(acc[2 * j]), bf_hi(av[j]) * gelu_f(acc[2 * j + 1]));
;             *(u32x4*)ap = wv;
; #pragma unroll
;             for (int rr = 0; rr < 3; ++rr) { L[rr] = M[rr]; M[rr] = R[rr]; }
;         }
	v_lshlrev_b32_e32 v110, 16, v94
	v_pk_fma_f32 v[166:167], v[92:93], v[166:167], s[84:85] op_sel_hi:[1,1,0]
	v_and_b32_e32 v111, 0xffff0000, v94
	v_pk_fma_f32 v[166:167], v[92:93], v[166:167], s[64:65] op_sel_hi:[1,1,0]
	v_lshlrev_b32_e32 v94, 16, v99
	v_pk_mul_f32 v[92:93], v[92:93], v[166:167]
	s_nop 0
	v_pk_mul_f32 v[92:93], v[96:97], v[92:93]
	s_nop 0
	v_pk_mul_f32 v[96:97], v[88:89], v[92:93]
	v_pk_fma_f32 v[88:89], v[88:89], v[92:93], v[88:89] neg_lo:[1,0,0] neg_hi:[1,0,0]
	v_pk_mul_f32 v[92:93], v[32:33], v[140:141]
	v_cndmask_b32_e64 v89, v89, v97, s[0:1]
	v_cndmask_b32_e32 v88, v88, v96, vcc
	v_pk_mul_f32 v[88:89], v[88:89], v[112:113]
	v_pk_fma_f32 v[92:93], v[40:41], v[126:127], v[92:93]
	v_cvt_pk_bf16_f32 v85, v88, v89
	v_pk_mul_f32 v[88:89], v[16:17], v[104:105]
	v_lshlrev_b32_e32 v112, 16, v86
	v_pk_fma_f32 v[88:89], v[0:1], v[100:101], v[88:89]
	v_lshlrev_b32_e32 v100, 16, v90
	v_and_b32_e32 v101, 0xffff0000, v90
	v_pk_fma_f32 v[88:89], v[24:25], v[100:101], v[88:89]
	v_and_b32_e32 v113, 0xffff0000, v86
	v_pk_add_f32 v[88:89], v[76:77], v[88:89]
	v_pk_fma_f32 v[92:93], v[48:49], v[112:113], v[92:93]
	s_nop 0
	v_pk_add_f32 v[88:89], v[88:89], v[92:93]
	v_pk_mul_f32 v[92:93], v[56:57], v[128:129]
	v_lshlrev_b32_e32 v128, 16, v98
	v_pk_fma_f32 v[92:93], v[64:65], v[118:119], v[92:93]
	v_and_b32_e32 v129, 0xffff0000, v98
	v_pk_fma_f32 v[92:93], v[72:73], v[110:111], v[92:93]
	s_nop 0
	v_pk_add_f32 v[88:89], v[88:89], v[92:93]
	s_nop 0
	v_fma_f32 v9, |v88|, s80, 1.0
	v_pk_mul_f32 v[96:97], v[88:89], v[88:89]
	v_rcp_f32_e32 v92, v9
	v_mul_f32_e32 v9, 0xbf38aa3b, v96
	v_exp_f32_e32 v96, v9
	v_fma_f32 v9, |v89|, s80, 1.0
	v_rcp_f32_e32 v93, v9
	v_mul_f32_e32 v9, 0xbf38aa3b, v97
	v_exp_f32_e32 v97, v9
	v_cmp_gt_f32_e32 vcc, 0, v88
	v_pk_fma_f32 v[140:141], v[92:93], s[68:69], v[170:171] op_sel_hi:[1,0,0]
	v_cmp_gt_f32_e64 s[0:1], 0, v89
	v_pk_fma_f32 v[140:141], v[92:93], v[140:141], s[44:45] op_sel_hi:[1,1,0]
	s_nop 0
	v_pk_fma_f32 v[140:141], v[92:93], v[140:141], s[84:85] op_sel_hi:[1,1,0]
	s_nop 0
	v_pk_fma_f32 v[140:141], v[92:93], v[140:141], s[64:65] op_sel_hi:[1,1,0]
	s_nop 0
	v_pk_mul_f32 v[92:93], v[92:93], v[140:141]
	s_nop 0
	v_pk_mul_f32 v[92:93], v[96:97], v[92:93]
	s_nop 0
	v_pk_mul_f32 v[96:97], v[88:89], v[92:93]
	v_pk_fma_f32 v[88:89], v[88:89], v[92:93], v[88:89] neg_lo:[1,0,0] neg_hi:[1,0,0]
	s_nop 0
	v_cndmask_b32_e64 v89, v89, v97, s[0:1]
	v_cndmask_b32_e32 v88, v88, v96, vcc
	v_pk_mul_f32 v[88:89], v[88:89], v[128:129]
	s_nop 0
	v_cvt_pk_bf16_f32 v86, v88, v89
	v_pk_mul_f32 v[88:89], v[18:19], v[102:103]
	s_nop 0
	v_pk_fma_f32 v[88:89], v[2:3], v[10:11], v[88:89]
	v_lshlrev_b32_e32 v10, 16, v91
	v_and_b32_e32 v11, 0xffff0000, v91
	v_pk_mul_f32 v[90:91], v[34:35], v[108:109]
	v_pk_fma_f32 v[88:89], v[26:27], v[10:11], v[88:89]
	v_pk_fma_f32 v[90:91], v[42:43], v[116:117], v[90:91]
	v_lshlrev_b32_e32 v108, 16, v87
	v_and_b32_e32 v109, 0xffff0000, v87
	v_pk_add_f32 v[88:89], v[78:79], v[88:89]
	v_pk_fma_f32 v[90:91], v[50:51], v[108:109], v[90:91]
	s_nop 0
	v_pk_add_f32 v[88:89], v[88:89], v[90:91]
	v_pk_mul_f32 v[90:91], v[58:59], v[106:107]
	v_lshlrev_b32_e32 v106, 16, v95
	v_pk_fma_f32 v[90:91], v[66:67], v[114:115], v[90:91]
	v_and_b32_e32 v107, 0xffff0000, v95
	v_pk_fma_f32 v[90:91], v[74:75], v[106:107], v[90:91]
	v_and_b32_e32 v95, 0xffff0000, v99
	v_pk_add_f32 v[88:89], v[88:89], v[90:91]
	s_nop 0
	v_fma_f32 v9, |v88|, s80, 1.0
	v_pk_mul_f32 v[92:93], v[88:89], v[88:89]
	v_rcp_f32_e32 v90, v9
	v_mul_f32_e32 v9, 0xbf38aa3b, v92
	v_exp_f32_e32 v92, v9
	v_fma_f32 v9, |v89|, s80, 1.0
	v_rcp_f32_e32 v91, v9
	v_mul_f32_e32 v9, 0xbf38aa3b, v93
	v_exp_f32_e32 v93, v9
	v_cmp_gt_f32_e32 vcc, 0, v88
	v_pk_fma_f32 v[96:97], v[90:91], s[68:69], v[170:171] op_sel_hi:[1,0,0]
	v_cmp_gt_f32_e64 s[0:1], 0, v89
	v_pk_fma_f32 v[96:97], v[90:91], v[96:97], s[44:45] op_sel_hi:[1,1,0]
	v_add_u32_e32 v9, -2, v188
	v_pk_fma_f32 v[96:97], v[90:91], v[96:97], s[84:85] op_sel_hi:[1,1,0]
	s_nop 0
	v_pk_fma_f32 v[96:97], v[90:91], v[96:97], s[64:65] op_sel_hi:[1,1,0]
	s_nop 0
	v_pk_mul_f32 v[90:91], v[90:91], v[96:97]
	s_nop 0
	v_pk_mul_f32 v[90:91], v[92:93], v[90:91]
	s_nop 0
	v_pk_mul_f32 v[92:93], v[88:89], v[90:91]
	v_pk_fma_f32 v[88:89], v[88:89], v[90:91], v[88:89] neg_lo:[1,0,0] neg_hi:[1,0,0]
	v_mov_b32_e32 v90, 0
	v_cndmask_b32_e64 v89, v89, v93, s[0:1]
	v_cndmask_b32_e32 v88, v88, v92, vcc
	v_pk_mul_f32 v[88:89], v[88:89], v[94:95]
	v_cmp_lt_u32_e64 s[0:1], v9, v187
	v_cvt_pk_bf16_f32 v87, v88, v89
	global_store_dwordx4 v[172:173], v[84:87], off offset:2048 nt
	s_and_b64 s[6:7], s[0:1], s[40:41]
	v_mov_b32_e32 v88, 0
	v_mov_b32_e32 v84, 0
	v_mov_b32_e32 v89, 0
	v_mov_b32_e32 v91, 0
	s_and_saveexec_b64 s[66:67], s[6:7]
	s_cbranch_execz .LBB0_751
	v_add_co_u32_e32 v86, vcc, 0x13a5d000, v124
	s_nop 1
	v_addc_co_u32_e32 v87, vcc, 0, v125, vcc

; __device__ void phase_conv(const Params& p, int l, int nrows) {
;     ...
;         for (int i = 0; i < 16; ++i) {
;             const bf16_t* np = gp + (size_t)(i + 1) * FF;
;             const bool v = (c0 + i + 1) < W;
;             R[0] = (v && up) ? *(const u32x4*)(np - (size_t)64 * FF) : zero; R[1] = v ? *(const u32x4*)np : zero; R[2] = (v && dn) ? *(const u32x4*)(np + (size_t)64 * FF) : zero;
;             float acc[8];
; #pragma unroll
;             for (int j = 0; j < 8; ++j) acc[j] = bias[j];
.LBB0_755:
	s_or_b64 exec, exec, s[66:67]
	v_add_co_u32_e32 v166, vcc, 0x7fb3000, v124
	v_pk_mul_f32 v[128:129], v[12:13], v[144:145]
	s_nop 0
	v_addc_co_u32_e32 v167, vcc, 0, v125, vcc
	v_pk_fma_f32 v[128:129], v[4:5], v[148:149], v[128:129]
	s_waitcnt vmcnt(1)
	v_mov_b64_e32 v[88:89], v[200:201]
	v_mov_b64_e32 v[90:91], v[202:203]
	v_mov_b64_e32 v[84:85], v[204:205]
	v_mov_b64_e32 v[86:87], v[206:207]
	v_mov_b64_e32 v[92:93], v[208:209]
	v_mov_b64_e32 v[94:95], v[210:211]
	v_mov_b64_e32 v[96:97], v[196:197]
	v_mov_b64_e32 v[98:99], v[198:199]
	v_add_u32_e32 v214, -1, v188
	v_cmp_lt_u32_e64 s[98:99], v214, v187
	s_add_u32 s100, s20, 0x7fb5400
	s_addc_u32 s101, s21, 0
	global_load_dwordx4 v[196:199], v192, s[100:101] nt
	v_mov_b32_e32 v200, 0
	v_mov_b32_e32 v201, 0
	v_mov_b32_e32 v202, 0
	v_mov_b32_e32 v203, 0
	v_mov_b32_e32 v204, 0
	v_mov_b32_e32 v205, 0
	v_mov_b32_e32 v206, 0
	v_mov_b32_e32 v207, 0
	v_mov_b32_e32 v208, 0
	v_mov_b32_e32 v209, 0
	v_mov_b32_e32 v210, 0
	v_mov_b32_e32 v211, 0
	s_add_u32 s10, s20, 0x13ab6a00
	s_addc_u32 s11, s21, 0
	s_and_saveexec_b64 s[22:23], s[98:99]
	global_load_dwordx4 v[204:207], v192, s[10:11]
	s_add_u32 s100, s20, 0x13a5ea00
	s_addc_u32 s101, s21, 0
	s_and_b64 exec, exec, s[40:41]
	global_load_dwordx4 v[200:203], v192, s[100:101]
	s_add_u32 s10, s20, 0x13b0ea00
	s_addc_u32 s11, s21, 0
	s_and_b64 exec, s[22:23], s[98:99]
	s_and_b64 exec, exec, s[42:43]
	global_load_dwordx4 v[208:211], v192, s[10:11]
	s_mov_b64 exec, s[22:23]
	v_lshlrev_b32_e32 v148, 16, v88
	v_and_b32_e32 v149, 0xffff0000, v88
	v_pk_mul_f32 v[140:141], v[28:29], v[164:165]
	v_pk_fma_f32 v[128:129], v[20:21], v[148:149], v[128:129]
	v_pk_fma_f32 v[140:141], v[36:37], v[156:157], v[140:141]
	v_lshlrev_b32_e32 v164, 16, v84
	v_and_b32_e32 v165, 0xffff0000, v84
	v_pk_add_f32 v[128:129], v[80:81], v[128:129]
	v_pk_fma_f32 v[140:141], v[44:45], v[164:165], v[140:141]
	v_mov_b64_e32 v[168:169], s[90:91]
	v_pk_add_f32 v[128:129], v[128:129], v[140:141]
	v_pk_mul_f32 v[140:141], v[52:53], v[162:163]
	v_lshlrev_b32_e32 v162, 16, v92
	v_pk_fma_f32 v[140:141], v[60:61], v[154:155], v[140:141]
	v_and_b32_e32 v163, 0xffff0000, v92
	v_pk_fma_f32 v[140:141], v[68:69], v[162:163], v[140:141]
	s_nop 0
	v_lshlrev_b32_e32 v172, 16, v96
	v_pk_add_f32 v[128:129], v[128:129], v[140:141]
	v_and_b32_e32 v173, 0xffff0000, v96
	v_fma_f32 v9, |v128|, s80, 1.0
	v_pk_mul_f32 v[170:171], v[128:129], v[128:129]
	v_rcp_f32_e32 v140, v9
	v_mul_f32_e32 v9, 0xbf38aa3b, v170
	v_exp_f32_e32 v170, v9
	v_fma_f32 v9, |v129|, s80, 1.0
	v_rcp_f32_e32 v141, v9
	v_mul_f32_e32 v9, 0xbf38aa3b, v171
	v_exp_f32_e32 v171, v9
	v_cmp_gt_f32_e32 vcc, 0, v128
	v_pk_fma_f32 v[174:175], v[140:141], s[68:69], v[168:169] op_sel_hi:[1,0,0]
	v_cmp_gt_f32_e64 s[0:1], 0, v129
	v_pk_fma_f32 v[174:175], v[140:141], v[174:175], s[44:45] op_sel_hi:[1,1,0]
	s_nop 0
	v_pk_fma_f32 v[174:175], v[140:141], v[174:175], s[84:85] op_sel_hi:[1,1,0]
	s_nop 0
	v_pk_fma_f32 v[174:175], v[140:141], v[174:175], s[64:65] op_sel_hi:[1,1,0]
	s_nop 0
	v_pk_mul_f32 v[140:141], v[140:141], v[174:175]
	s_nop 0
	v_pk_mul_f32 v[140:141], v[170:171], v[140:141]
	s_nop 0
	v_pk_mul_f32 v[170:171], v[128:129], v[140:141]
	v_pk_fma_f32 v[128:129], v[128:129], v[140:141], v[128:129] neg_lo:[1,0,0] neg_hi:[1,0,0]
	v_lshlrev_b32_e32 v140, 16, v97
	v_cndmask_b32_e64 v129, v129, v171, s[0:1]
	v_cndmask_b32_e32 v128, v128, v170, vcc
	v_pk_mul_f32 v[128:129], v[128:129], v[172:173]
	v_and_b32_e32 v141, 0xffff0000, v97
	v_cvt_pk_bf16_f32 v84, v128, v129
	v_pk_mul_f32 v[128:129], v[14:15], v[142:143]
	s_nop 0
	v_pk_fma_f32 v[128:129], v[6:7], v[146:147], v[128:129]
	v_lshlrev_b32_e32 v146, 16, v89
	v_and_b32_e32 v147, 0xffff0000, v89
	v_pk_fma_f32 v[88:89], v[22:23], v[146:147], v[128:129]
	v_pk_mul_f32 v[128:129], v[30:31], v[160:161]
	v_lshlrev_b32_e32 v160, 16, v85
	v_pk_fma_f32 v[128:129], v[38:39], v[152:153], v[128:129]
	v_and_b32_e32 v161, 0xffff0000, v85
	v_pk_add_f32 v[88:89], v[82:83], v[88:89]
	v_pk_fma_f32 v[128:129], v[46:47], v[160:161], v[128:129]
	s_nop 0
	v_pk_add_f32 v[88:89], v[88:89], v[128:129]
	v_pk_mul_f32 v[128:129], v[54:55], v[158:159]
	v_lshlrev_b32_e32 v158, 16, v93
	v_pk_fma_f32 v[128:129], v[62:63], v[150:151], v[128:129]
	v_and_b32_e32 v159, 0xffff0000, v93
	v_pk_fma_f32 v[92:93], v[70:71], v[158:159], v[128:129]
	s_nop 0
	v_pk_add_f32 v[88:89], v[88:89], v[92:93]
	s_nop 0
	v_fma_f32 v9, |v88|, s80, 1.0
	v_pk_mul_f32 v[128:129], v[88:89], v[88:89]
	v_rcp_f32_e32 v92, v9
	v_mul_f32_e32 v9, 0xbf38aa3b, v128
	v_exp_f32_e32 v96, v9
	v_fma_f32 v9, |v89|, s80, 1.0
	v_rcp_f32_e32 v93, v9
	v_mul_f32_e32 v9, 0xbf38aa3b, v129
	v_exp_f32_e32 v97, v9
	v_cmp_gt_f32_e32 vcc, 0, v88
	v_pk_fma_f32 v[170:171], v[92:93], s[68:69], v[168:169] op_sel_hi:[1,0,0]
	v_cmp_gt_f32_e64 s[0:1], 0, v89
; __device__ __forceinline__ unsigned pk_bf16(float a, float b) { f32x2 v = {a, b}; bf2_t r = __builtin_convertvector(v, bf2_t); return __builtin_bit_cast(unsigned, r); }
; __device__ __forceinline__ float bf_lo(unsigned u) { return __uint_as_float(u << 16); }
; __device__ __forceinline__ float bf_hi(unsigned u) { return __uint_as_float(u & 0xffff0000u); }
; __device__ void phase_conv(const Params& p, int l, int nrows) {
;     ...
; #pragma unroll
;             for (int rr = 0; rr < 3; ++rr) {
; #pragma unroll
;                 for (int j = 0; j < 4; ++j) {
;                     acc[2 * j] += bf_lo(L[rr][j]) * tp[rr * 3 + 0][2 * j] + bf_lo(M[rr][j]) * tp[rr * 3 + 1][2 * j] + bf_lo(R[rr][j]) * tp[rr * 3 + 2][2 * j];
;                     acc[2 * j + 1] += bf_hi(L[rr][j]) * tp[rr * 3 + 0][2 * j + 1] + bf_hi(M[rr][j]) * tp[rr * 3 + 1][2 * j + 1] + bf_hi(R[rr][j]) * tp[rr * 3 + 2][2 * j + 1];
;                 }
;             }
;             bf16_t* ap = Aup + (size_t)(tok0 + i) * FF + f0;
;             const u32x4 av = __builtin_nontemporal_load((const u32x4*)ap);
;             u32x4 wv;
; #pragma unroll
;             for (int j = 0; j < 4; ++j) wv[j] = pk_bf16(bf_lo(av[j]) * gelu_f(acc[2 * j]), bf_hi(av[j]) * gelu_f(acc[2 * j + 1]));
;             *(u32x4*)ap = wv;
; #pragma unroll
;             for (int rr = 0; rr < 3; ++rr) { L[rr] = M[rr]; M[rr] = R[rr]; }
;         }
	v_pk_fma_f32 v[170:171], v[92:93], v[170:171], s[44:45] op_sel_hi:[1,1,0]
	v_lshlrev_b32_e32 v128, 16, v90
	v_pk_fma_f32 v[170:171], v[92:93], v[170:171], s[84:85] op_sel_hi:[1,1,0]
	v_and_b32_e32 v129, 0xffff0000, v90
	v_pk_fma_f32 v[170:171], v[92:93], v[170:171], s[64:65] op_sel_hi:[1,1,0]
	s_nop 0
	v_pk_mul_f32 v[92:93], v[92:93], v[170:171]
	s_nop 0
	v_pk_mul_f32 v[92:93], v[96:97], v[92:93]
	s_nop 0
	v_pk_mul_f32 v[96:97], v[88:89], v[92:93]
	v_pk_fma_f32 v[88:89], v[88:89], v[92:93], v[88:89] neg_lo:[1,0,0] neg_hi:[1,0,0]
	v_pk_mul_f32 v[92:93], v[32:33], v[126:127]
	v_cndmask_b32_e64 v89, v89, v97, s[0:1]
	v_cndmask_b32_e32 v88, v88, v96, vcc
	v_pk_mul_f32 v[88:89], v[88:89], v[140:141]
	v_pk_fma_f32 v[92:93], v[40:41], v[112:113], v[92:93]
	v_cvt_pk_bf16_f32 v85, v88, v89
	v_pk_mul_f32 v[88:89], v[16:17], v[100:101]
	v_lshlrev_b32_e32 v140, 16, v86
	v_pk_fma_f32 v[88:89], v[0:1], v[104:105], v[88:89]
	v_and_b32_e32 v141, 0xffff0000, v86
	v_pk_fma_f32 v[88:89], v[24:25], v[128:129], v[88:89]
	v_pk_fma_f32 v[92:93], v[48:49], v[140:141], v[92:93]
	v_pk_add_f32 v[88:89], v[76:77], v[88:89]
	v_lshlrev_b32_e32 v126, 16, v94
	v_pk_add_f32 v[88:89], v[88:89], v[92:93]
	v_pk_mul_f32 v[92:93], v[56:57], v[118:119]
	v_and_b32_e32 v127, 0xffff0000, v94
	v_pk_fma_f32 v[92:93], v[64:65], v[110:111], v[92:93]
	v_lshlrev_b32_e32 v104, 16, v98
	v_pk_fma_f32 v[92:93], v[72:73], v[126:127], v[92:93]
	v_and_b32_e32 v105, 0xffff0000, v98
	v_pk_add_f32 v[88:89], v[88:89], v[92:93]
	v_lshlrev_b32_e32 v94, 16, v99
	v_fma_f32 v9, |v88|, s80, 1.0
	v_pk_mul_f32 v[96:97], v[88:89], v[88:89]
	v_rcp_f32_e32 v92, v9
	v_mul_f32_e32 v9, 0xbf38aa3b, v96
	v_exp_f32_e32 v96, v9
	v_fma_f32 v9, |v89|, s80, 1.0
	v_rcp_f32_e32 v93, v9
	v_mul_f32_e32 v9, 0xbf38aa3b, v97
	v_exp_f32_e32 v97, v9
	v_cmp_gt_f32_e32 vcc, 0, v88
	v_pk_fma_f32 v[118:119], v[92:93], s[68:69], v[168:169] op_sel_hi:[1,0,0]
	v_cmp_gt_f32_e64 s[0:1], 0, v89
	v_pk_fma_f32 v[118:119], v[92:93], v[118:119], s[44:45] op_sel_hi:[1,1,0]
	s_nop 0
	v_pk_fma_f32 v[118:119], v[92:93], v[118:119], s[84:85] op_sel_hi:[1,1,0]
	s_nop 0
	v_pk_fma_f32 v[118:119], v[92:93], v[118:119], s[64:65] op_sel_hi:[1,1,0]
	s_nop 0
	v_pk_mul_f32 v[92:93], v[92:93], v[118:119]
	v_lshlrev_b32_e32 v118, 16, v91
	v_pk_mul_f32 v[92:93], v[96:97], v[92:93]
	v_and_b32_e32 v119, 0xffff0000, v91
	v_pk_mul_f32 v[96:97], v[88:89], v[92:93]
	v_pk_fma_f32 v[88:89], v[88:89], v[92:93], v[88:89] neg_lo:[1,0,0] neg_hi:[1,0,0]
	v_pk_mul_f32 v[90:91], v[34:35], v[116:117]
	v_cndmask_b32_e64 v89, v89, v97, s[0:1]
	v_cndmask_b32_e32 v88, v88, v96, vcc
	v_pk_mul_f32 v[88:89], v[88:89], v[104:105]
	v_pk_fma_f32 v[90:91], v[42:43], v[108:109], v[90:91]
	v_cvt_pk_bf16_f32 v86, v88, v89
	v_pk_mul_f32 v[88:89], v[18:19], v[10:11]
	v_lshlrev_b32_e32 v116, 16, v87
	v_pk_fma_f32 v[88:89], v[2:3], v[102:103], v[88:89]
	v_and_b32_e32 v117, 0xffff0000, v87
	v_pk_fma_f32 v[88:89], v[26:27], v[118:119], v[88:89]
	v_pk_fma_f32 v[90:91], v[50:51], v[116:117], v[90:91]
	v_pk_add_f32 v[88:89], v[78:79], v[88:89]
	s_nop 0
	v_pk_add_f32 v[88:89], v[88:89], v[90:91]
	v_pk_mul_f32 v[90:91], v[58:59], v[114:115]
	v_lshlrev_b32_e32 v114, 16, v95
	v_pk_fma_f32 v[90:91], v[66:67], v[106:107], v[90:91]
	v_and_b32_e32 v115, 0xffff0000, v95
	v_pk_fma_f32 v[90:91], v[74:75], v[114:115], v[90:91]
	v_and_b32_e32 v95, 0xffff0000, v99
	v_pk_add_f32 v[88:89], v[88:89], v[90:91]
	s_nop 0
	v_fma_f32 v9, |v88|, s80, 1.0
	v_pk_mul_f32 v[92:93], v[88:89], v[88:89]
	v_rcp_f32_e32 v90, v9
	v_mul_f32_e32 v9, 0xbf38aa3b, v92
	v_exp_f32_e32 v92, v9
	v_fma_f32 v9, |v89|, s80, 1.0
	v_rcp_f32_e32 v91, v9
	v_mul_f32_e32 v9, 0xbf38aa3b, v93
	v_exp_f32_e32 v93, v9
	v_cmp_gt_f32_e32 vcc, 0, v88
	v_pk_fma_f32 v[96:97], v[90:91], s[68:69], v[168:169] op_sel_hi:[1,0,0]
	v_cmp_gt_f32_e64 s[0:1], 0, v89
	v_pk_fma_f32 v[96:97], v[90:91], v[96:97], s[44:45] op_sel_hi:[1,1,0]
	v_add_u32_e32 v9, -1, v188
	v_pk_fma_f32 v[96:97], v[90:91], v[96:97], s[84:85] op_sel_hi:[1,1,0]
	s_nop 0
	v_pk_fma_f32 v[96:97], v[90:91], v[96:97], s[64:65] op_sel_hi:[1,1,0]
	s_nop 0
	v_pk_mul_f32 v[90:91], v[90:91], v[96:97]
	s_nop 0
	v_pk_mul_f32 v[90:91], v[92:93], v[90:91]
	s_nop 0
	v_pk_mul_f32 v[92:93], v[88:89], v[90:91]
	v_pk_fma_f32 v[88:89], v[88:89], v[90:91], v[88:89] neg_lo:[1,0,0] neg_hi:[1,0,0]
	s_nop 0
	v_cndmask_b32_e64 v89, v89, v93, s[0:1]
	v_cndmask_b32_e32 v88, v88, v92, vcc
	v_pk_mul_f32 v[88:89], v[88:89], v[94:95]
	v_cmp_lt_u32_e64 s[0:1], v9, v187
	v_cvt_pk_bf16_f32 v87, v88, v89
	global_store_dwordx4 v[166:167], v[84:87], off offset:3584 nt
	s_and_b64 s[6:7], s[0:1], s[40:41]
	v_mov_b32_e32 v92, 0
	v_mov_b32_e32 v84, 0
	v_mov_b32_e32 v93, 0
	v_mov_b32_e32 v94, 0
	v_mov_b32_e32 v95, 0
	s_and_saveexec_b64 s[66:67], s[6:7]
	s_cbranch_execz .LBB0_757
	v_add_co_u32_e32 v86, vcc, 0x13a5e000, v124
	s_nop 1
	v_addc_co_u32_e32 v87, vcc, 0, v125, vcc

; __device__ void phase_conv(const Params& p, int l, int nrows) {
;     ...
;         for (int i = 0; i < 16; ++i) {
;             const bf16_t* np = gp + (size_t)(i + 1) * FF;
;             const bool v = (c0 + i + 1) < W;
;             R[0] = (v && up) ? *(const u32x4*)(np - (size_t)64 * FF) : zero; R[1] = v ? *(const u32x4*)np : zero; R[2] = (v && dn) ? *(const u32x4*)(np + (size_t)64 * FF) : zero;
;             float acc[8];
; #pragma unroll
;             for (int j = 0; j < 8; ++j) acc[j] = bias[j];
.LBB0_761:
	s_or_b64 exec, exec, s[66:67]
	v_add_co_u32_e32 v102, vcc, 0x7fb5000, v124
	v_pk_mul_f32 v[104:105], v[12:13], v[148:149]
	s_nop 0
	v_addc_co_u32_e32 v103, vcc, 0, v125, vcc
	v_pk_fma_f32 v[104:105], v[4:5], v[144:145], v[104:105]
	s_waitcnt vmcnt(1)
	v_mov_b64_e32 v[92:93], v[200:201]
	v_mov_b64_e32 v[94:95], v[202:203]
	v_mov_b64_e32 v[84:85], v[204:205]
	v_mov_b64_e32 v[86:87], v[206:207]
	v_mov_b64_e32 v[88:89], v[208:209]
	v_mov_b64_e32 v[90:91], v[210:211]
	v_mov_b64_e32 v[96:97], v[196:197]
	v_mov_b64_e32 v[98:99], v[198:199]
	v_add_u32_e32 v214, 0, v188
	v_cmp_lt_u32_e64 s[98:99], v214, v187
	s_add_u32 s100, s20, 0x7fb6a00
	s_addc_u32 s101, s21, 0
	global_load_dwordx4 v[196:199], v192, s[100:101] nt
	v_mov_b32_e32 v200, 0
	v_mov_b32_e32 v201, 0
	v_mov_b32_e32 v202, 0
	v_mov_b32_e32 v203, 0
	v_mov_b32_e32 v204, 0
	v_mov_b32_e32 v205, 0
	v_mov_b32_e32 v206, 0
	v_mov_b32_e32 v207, 0
	v_mov_b32_e32 v208, 0
	v_mov_b32_e32 v209, 0
	v_mov_b32_e32 v210, 0
	v_mov_b32_e32 v211, 0
	s_add_u32 s10, s20, 0x13ab8000
	s_addc_u32 s11, s21, 0
	s_and_saveexec_b64 s[22:23], s[98:99]
	global_load_dwordx4 v[204:207], v192, s[10:11]
	s_add_u32 s100, s20, 0x13a60000
	s_addc_u32 s101, s21, 0
	s_and_b64 exec, exec, s[40:41]
	global_load_dwordx4 v[200:203], v192, s[100:101]
	s_add_u32 s10, s20, 0x13b10000
	s_addc_u32 s11, s21, 0
	s_and_b64 exec, s[22:23], s[98:99]
	s_and_b64 exec, exec, s[42:43]
	global_load_dwordx4 v[208:211], v192, s[10:11]
	s_mov_b64 exec, s[22:23]
	v_lshlrev_b32_e32 v174, 16, v92
	v_and_b32_e32 v175, 0xffff0000, v92
	v_pk_mul_f32 v[144:145], v[28:29], v[156:157]
	v_pk_fma_f32 v[104:105], v[20:21], v[174:175], v[104:105]
	v_pk_fma_f32 v[144:145], v[36:37], v[164:165], v[144:145]
	v_lshlrev_b32_e32 v170, 16, v84
	v_and_b32_e32 v171, 0xffff0000, v84
	v_pk_add_f32 v[104:105], v[80:81], v[104:105]
	v_pk_fma_f32 v[144:145], v[44:45], v[170:171], v[144:145]
	v_lshlrev_b32_e32 v168, 16, v88
	v_pk_add_f32 v[104:105], v[104:105], v[144:145]
	v_pk_mul_f32 v[144:145], v[52:53], v[154:155]
	v_and_b32_e32 v169, 0xffff0000, v88
	v_pk_fma_f32 v[144:145], v[60:61], v[162:163], v[144:145]
	v_pk_mul_f32 v[112:113], v[32:33], v[112:113]
	v_pk_fma_f32 v[144:145], v[68:69], v[168:169], v[144:145]
	v_pk_fma_f32 v[112:113], v[40:41], v[140:141], v[112:113]
	v_pk_add_f32 v[144:145], v[104:105], v[144:145]
	v_mov_b64_e32 v[104:105], s[90:91]
	v_fma_f32 v9, |v144|, s80, 1.0
	v_pk_mul_f32 v[156:157], v[144:145], v[144:145]
	v_rcp_f32_e32 v154, v9
	v_mul_f32_e32 v9, 0xbf38aa3b, v156
	v_exp_f32_e32 v156, v9
	v_fma_f32 v9, |v145|, s80, 1.0
	v_rcp_f32_e32 v155, v9
	v_mul_f32_e32 v9, 0xbf38aa3b, v157
	v_exp_f32_e32 v157, v9
	v_cmp_gt_f32_e32 vcc, 0, v144
	v_pk_fma_f32 v[172:173], v[154:155], s[68:69], v[104:105] op_sel_hi:[1,0,0]
	v_cmp_gt_f32_e64 s[0:1], 0, v145
	v_pk_fma_f32 v[172:173], v[154:155], v[172:173], s[44:45] op_sel_hi:[1,1,0]
	v_pk_mul_f32 v[110:111], v[56:57], v[110:111]
	v_pk_fma_f32 v[172:173], v[154:155], v[172:173], s[84:85] op_sel_hi:[1,1,0]
	v_pk_fma_f32 v[110:111], v[64:65], v[126:127], v[110:111]
	v_pk_fma_f32 v[172:173], v[154:155], v[172:173], s[64:65] op_sel_hi:[1,1,0]
	s_nop 0
	v_lshlrev_b32_e32 v166, 16, v96
	v_pk_mul_f32 v[154:155], v[154:155], v[172:173]
	v_and_b32_e32 v167, 0xffff0000, v96
	v_pk_mul_f32 v[154:155], v[156:157], v[154:155]
	v_lshlrev_b32_e32 v172, 16, v93
	v_pk_mul_f32 v[156:157], v[144:145], v[154:155]
	v_pk_fma_f32 v[144:145], v[144:145], v[154:155], v[144:145] neg_lo:[1,0,0] neg_hi:[1,0,0]
	v_and_b32_e32 v173, 0xffff0000, v93
	v_cndmask_b32_e64 v145, v145, v157, s[0:1]
	v_cndmask_b32_e32 v144, v144, v156, vcc
	v_pk_mul_f32 v[144:145], v[144:145], v[166:167]
	v_lshlrev_b32_e32 v166, 16, v85
	v_cvt_pk_bf16_f32 v96, v144, v145
	v_pk_mul_f32 v[144:145], v[14:15], v[146:147]
	v_and_b32_e32 v167, 0xffff0000, v85
	v_pk_fma_f32 v[142:143], v[6:7], v[142:143], v[144:145]
	v_pk_mul_f32 v[144:145], v[30:31], v[152:153]
	v_pk_fma_f32 v[142:143], v[22:23], v[172:173], v[142:143]
	v_pk_fma_f32 v[144:145], v[38:39], v[160:161], v[144:145]
	v_pk_add_f32 v[142:143], v[82:83], v[142:143]
	v_pk_fma_f32 v[144:145], v[46:47], v[166:167], v[144:145]
	v_lshlrev_b32_e32 v156, 16, v89
	v_pk_add_f32 v[142:143], v[142:143], v[144:145]
	v_pk_mul_f32 v[144:145], v[54:55], v[150:151]
	v_and_b32_e32 v157, 0xffff0000, v89
	v_pk_fma_f32 v[144:145], v[62:63], v[158:159], v[144:145]
	v_lshlrev_b32_e32 v152, 16, v97
	v_pk_fma_f32 v[144:145], v[70:71], v[156:157], v[144:145]
	v_and_b32_e32 v153, 0xffff0000, v97
	v_pk_add_f32 v[142:143], v[142:143], v[144:145]
	s_nop 0
	v_fma_f32 v9, |v142|, s80, 1.0
	v_pk_mul_f32 v[150:151], v[142:143], v[142:143]
	v_rcp_f32_e32 v144, v9
	v_mul_f32_e32 v9, 0xbf38aa3b, v150
	v_exp_f32_e32 v150, v9
	v_fma_f32 v9, |v143|, s80, 1.0
	v_rcp_f32_e32 v145, v9
	v_mul_f32_e32 v9, 0xbf38aa3b, v151
	v_exp_f32_e32 v151, v9
	v_cmp_gt_f32_e32 vcc, 0, v142
	v_pk_fma_f32 v[154:155], v[144:145], s[68:69], v[104:105] op_sel_hi:[1,0,0]
; __device__ __forceinline__ unsigned pk_bf16(float a, float b) { f32x2 v = {a, b}; bf2_t r = __builtin_convertvector(v, bf2_t); return __builtin_bit_cast(unsigned, r); }
; __device__ __forceinline__ float bf_lo(unsigned u) { return __uint_as_float(u << 16); }
; __device__ __forceinline__ float bf_hi(unsigned u) { return __uint_as_float(u & 0xffff0000u); }
; __device__ void phase_conv(const Params& p, int l, int nrows) {
;     ...
; #pragma unroll
;             for (int rr = 0; rr < 3; ++rr) {
; #pragma unroll
;                 for (int j = 0; j < 4; ++j) {
;                     acc[2 * j] += bf_lo(L[rr][j]) * tp[rr * 3 + 0][2 * j] + bf_lo(M[rr][j]) * tp[rr * 3 + 1][2 * j] + bf_lo(R[rr][j]) * tp[rr * 3 + 2][2 * j];
;                     acc[2 * j + 1] += bf_hi(L[rr][j]) * tp[rr * 3 + 0][2 * j + 1] + bf_hi(M[rr][j]) * tp[rr * 3 + 1][2 * j + 1] + bf_hi(R[rr][j]) * tp[rr * 3 + 2][2 * j + 1];
;                 }
;             }
;             bf16_t* ap = Aup + (size_t)(tok0 + i) * FF + f0;
;             const u32x4 av = __builtin_nontemporal_load((const u32x4*)ap);
;             u32x4 wv;
; #pragma unroll
;             for (int j = 0; j < 4; ++j) wv[j] = pk_bf16(bf_lo(av[j]) * gelu_f(acc[2 * j]), bf_hi(av[j]) * gelu_f(acc[2 * j + 1]));
;             *(u32x4*)ap = wv;
; #pragma unroll
;             for (int rr = 0; rr < 3; ++rr) { L[rr] = M[rr]; M[rr] = R[rr]; }
;         }
	v_cmp_gt_f32_e64 s[0:1], 0, v143
	v_pk_fma_f32 v[154:155], v[144:145], v[154:155], s[44:45] op_sel_hi:[1,1,0]
	s_nop 0
	v_pk_fma_f32 v[154:155], v[144:145], v[154:155], s[84:85] op_sel_hi:[1,1,0]
	s_nop 0
	v_pk_fma_f32 v[154:155], v[144:145], v[154:155], s[64:65] op_sel_hi:[1,1,0]
	s_nop 0
	v_pk_mul_f32 v[144:145], v[144:145], v[154:155]
	v_lshlrev_b32_e32 v154, 16, v94
	v_pk_mul_f32 v[144:145], v[150:151], v[144:145]
	v_and_b32_e32 v155, 0xffff0000, v94
	v_pk_mul_f32 v[150:151], v[142:143], v[144:145]
	v_pk_fma_f32 v[142:143], v[142:143], v[144:145], v[142:143] neg_lo:[1,0,0] neg_hi:[1,0,0]
	v_lshlrev_b32_e32 v144, 16, v90
	v_cndmask_b32_e64 v143, v143, v151, s[0:1]
	v_cndmask_b32_e32 v142, v142, v150, vcc
	v_pk_mul_f32 v[142:143], v[142:143], v[152:153]
	v_lshlrev_b32_e32 v150, 16, v86
	v_cvt_pk_bf16_f32 v97, v142, v143
	v_pk_mul_f32 v[142:143], v[16:17], v[128:129]
	v_and_b32_e32 v151, 0xffff0000, v86
	v_pk_fma_f32 v[100:101], v[0:1], v[100:101], v[142:143]
	v_pk_fma_f32 v[112:113], v[48:49], v[150:151], v[112:113]
	v_pk_fma_f32 v[100:101], v[24:25], v[154:155], v[100:101]
	v_and_b32_e32 v145, 0xffff0000, v90
	v_pk_add_f32 v[100:101], v[76:77], v[100:101]
	v_pk_fma_f32 v[110:111], v[72:73], v[144:145], v[110:111]
	v_pk_add_f32 v[100:101], v[100:101], v[112:113]
	v_lshlrev_b32_e32 v142, 16, v98
	v_pk_add_f32 v[100:101], v[100:101], v[110:111]
	v_and_b32_e32 v143, 0xffff0000, v98
	v_fma_f32 v9, |v100|, s80, 1.0
	v_pk_mul_f32 v[112:113], v[100:101], v[100:101]
	v_rcp_f32_e32 v110, v9
	v_mul_f32_e32 v9, 0xbf38aa3b, v112
	v_exp_f32_e32 v112, v9
	v_fma_f32 v9, |v101|, s80, 1.0
	v_rcp_f32_e32 v111, v9
	v_mul_f32_e32 v9, 0xbf38aa3b, v113
	v_exp_f32_e32 v113, v9
	v_cmp_gt_f32_e32 vcc, 0, v100
	v_pk_fma_f32 v[152:153], v[110:111], s[68:69], v[104:105] op_sel_hi:[1,0,0]
	v_cmp_gt_f32_e64 s[0:1], 0, v101
	v_pk_fma_f32 v[152:153], v[110:111], v[152:153], s[44:45] op_sel_hi:[1,1,0]
	s_nop 0
	v_pk_fma_f32 v[152:153], v[110:111], v[152:153], s[84:85] op_sel_hi:[1,1,0]
	s_nop 0
	v_pk_fma_f32 v[152:153], v[110:111], v[152:153], s[64:65] op_sel_hi:[1,1,0]
	s_nop 0
	v_pk_mul_f32 v[110:111], v[110:111], v[152:153]
	v_lshlrev_b32_e32 v152, 16, v95
	v_pk_mul_f32 v[110:111], v[112:113], v[110:111]
	v_and_b32_e32 v153, 0xffff0000, v95
	v_pk_mul_f32 v[112:113], v[100:101], v[110:111]
	v_pk_fma_f32 v[100:101], v[100:101], v[110:111], v[100:101] neg_lo:[1,0,0] neg_hi:[1,0,0]
	s_nop 0
	v_cndmask_b32_e64 v101, v101, v113, s[0:1]
	v_cndmask_b32_e32 v100, v100, v112, vcc
	v_pk_mul_f32 v[100:101], v[100:101], v[142:143]
	v_lshlrev_b32_e32 v142, 16, v87
	v_cvt_pk_bf16_f32 v98, v100, v101
	v_pk_mul_f32 v[100:101], v[18:19], v[118:119]
	v_and_b32_e32 v143, 0xffff0000, v87
	v_pk_fma_f32 v[10:11], v[2:3], v[10:11], v[100:101]
	v_pk_mul_f32 v[100:101], v[34:35], v[108:109]
	v_pk_fma_f32 v[10:11], v[26:27], v[152:153], v[10:11]
	v_pk_fma_f32 v[100:101], v[42:43], v[116:117], v[100:101]
	v_pk_add_f32 v[10:11], v[78:79], v[10:11]
	v_pk_fma_f32 v[100:101], v[50:51], v[142:143], v[100:101]
	v_lshlrev_b32_e32 v112, 16, v91
	v_pk_add_f32 v[10:11], v[10:11], v[100:101]
	v_pk_mul_f32 v[100:101], v[58:59], v[106:107]
	v_and_b32_e32 v113, 0xffff0000, v91
	v_pk_fma_f32 v[100:101], v[66:67], v[114:115], v[100:101]
	v_lshlrev_b32_e32 v108, 16, v99
	v_pk_fma_f32 v[100:101], v[74:75], v[112:113], v[100:101]
	v_and_b32_e32 v109, 0xffff0000, v99
	v_pk_add_f32 v[10:11], v[10:11], v[100:101]
	s_nop 0
	v_fma_f32 v9, |v10|, s80, 1.0
	v_pk_mul_f32 v[106:107], v[10:11], v[10:11]
	v_rcp_f32_e32 v100, v9
	v_mul_f32_e32 v9, 0xbf38aa3b, v106
	v_exp_f32_e32 v106, v9
	v_fma_f32 v9, |v11|, s80, 1.0
	v_rcp_f32_e32 v101, v9
	v_mul_f32_e32 v9, 0xbf38aa3b, v107
	v_exp_f32_e32 v107, v9
	v_cmp_gt_f32_e32 vcc, 0, v10
	v_pk_fma_f32 v[104:105], v[100:101], s[68:69], v[104:105] op_sel_hi:[1,0,0]
	v_cmp_gt_f32_e64 s[0:1], 0, v11
	v_pk_fma_f32 v[104:105], v[100:101], v[104:105], s[44:45] op_sel_hi:[1,1,0]
	s_nop 0
	v_pk_fma_f32 v[104:105], v[100:101], v[104:105], s[84:85] op_sel_hi:[1,1,0]
	s_nop 0
	v_pk_fma_f32 v[104:105], v[100:101], v[104:105], s[64:65] op_sel_hi:[1,1,0]
	s_nop 0
	v_pk_mul_f32 v[100:101], v[100:101], v[104:105]
	s_nop 0
	v_pk_mul_f32 v[100:101], v[106:107], v[100:101]
	v_mov_b32_e32 v106, 0
	v_pk_mul_f32 v[104:105], v[10:11], v[100:101]
	v_pk_fma_f32 v[10:11], v[10:11], v[100:101], v[10:11] neg_lo:[1,0,0] neg_hi:[1,0,0]
	v_mov_b32_e32 v107, 0
	v_cndmask_b32_e64 v11, v11, v105, s[0:1]
	v_cndmask_b32_e32 v10, v10, v104, vcc
	v_pk_mul_f32 v[10:11], v[10:11], v[108:109]
	v_cmp_lt_u32_e64 s[0:1], v188, v187
	v_cvt_pk_bf16_f32 v99, v10, v11
	global_store_dwordx4 v[102:103], v[96:99], off offset:1024 nt
	s_and_b64 s[6:7], s[0:1], s[40:41]
	v_mov_b32_e32 v104, 0
	v_mov_b32_e32 v96, 0
	v_mov_b32_e32 v105, 0
	s_and_saveexec_b64 s[66:67], s[6:7]
	s_cbranch_execz .LBB0_763
	v_add_co_u32_e32 v10, vcc, 0x13a60000, v124
	s_nop 1
	v_addc_co_u32_e32 v11, vcc, 0, v125, vcc
